# strategy 7.4: one static s_setprio 1 for waves 4-7 across both attention tile loops (on top of v41)
# speedup vs baseline: 1.0006x; 1.0006x over previous
; __device__ __forceinline__ float bflo(unsigned w) { return __uint_as_float(w << 16); }
; __device__ __forceinline__ float bfhi(unsigned w) { return __uint_as_float(w & 0xffff0000u); }
; __device__ __forceinline__ float pairsum(float v) { auto rr = __builtin_amdgcn_permlane32_swap(__float_as_uint(v), __float_as_uint(v), false, false); return __uint_as_float(rr[0]) + __uint_as_float(rr[1]); }
;     constexpr int ND = (MODE == 2) ? 6 : 4, QP = 1536;
;     const int r32 = lane & 31, hi = lane >> 5;
; #pragma unroll
;     for (int qb = 0; qb < 2; ++qb) {
;         __builtin_amdgcn_sched_barrier(0);
;         const bf16_t* src = U.q + (size_t)(32 * qb + r32) * QP + 8 * hi;
;         u32x4 raw[ND];
; #pragma unroll
;         for (int d0 = 0; d0 < ND; ++d0) raw[d0] = *(const u32x4*)(src + 16 * d0);
;         int pos = U.tq0 + 32 * qb + r32; asm volatile("" : "+v"(pos));
;         if constexpr (MODE == 1) {
; #pragma unroll
;             for (int d0 = 0; d0 < ND; ++d0) qf[qb][d0] = __builtin_bit_cast(bf16x8, raw[d0]);
;         } else if constexpr (MODE == 0) {
;             float v[4][8]; float ss = 0.f;
; #pragma unroll
;             for (int d0 = 0; d0 < 4; ++d0)
; #pragma unroll
;                 for (int j = 0; j < 4; ++j) { const unsigned w = raw[d0][j]; v[d0][2 * j] = bflo(w); v[d0][2 * j + 1] = bfhi(w); ss += v[d0][2 * j] * v[d0][2 * j] + v[d0][2 * j + 1] * v[d0][2 * j + 1]; }
;             ss = pairsum(ss);
;             const float rstd = rsqrtf(ss * (1.0f / 64.0f) + EPSN) * C2_64;
; #pragma unroll
;             for (int d0 = 0; d0 < 4; ++d0)
; #pragma unroll
;                 for (int j = 0; j < 8; ++j) v[d0][j] *= rstd * U.gain[16 * d0 + 8 * hi + j];
;             const int row = pos >> 6, col = pos & 63;
; #pragma unroll
;             for (int j = 0; j < 8; ++j) {
;                 __builtin_amdgcn_sched_barrier(0);
;                 const float fi = hi ? invf_c(8 + j) : invf_c(j); float c, s;
;                 rope_cs(row, fi, c, s); { const float x1 = v[0][j], x2 = v[1][j]; v[0][j] = x1 * c - x2 * s; v[1][j] = x2 * c + x1 * s; }
;                 rope_cs(col, fi, c, s); { const float x1 = v[2][j], x2 = v[3][j]; v[2][j] = x1 * c - x2 * s; v[3][j] = x2 * c + x1 * s; }
;             }
.LBB0_436:
	s_add_u32 s46, s12, s46
	s_addc_u32 s47, s13, s47
	s_add_i32 s87, s87, s86
	s_add_u32 s4, s53, s88
	s_addc_u32 s5, s54, s87
	s_lshl_b32 s6, s85, 1
	s_add_u32 s10, s4, s6
	s_addc_u32 s11, s5, 0
	s_lshl_b64 s[6:7], s[44:45], 22
	s_add_u32 s4, s55, s6
	s_addc_u32 s5, s56, s7
	s_lshl_b32 s33, s84, 1
	s_add_u32 s4, s4, s33
	s_load_dwordx2 s[8:9], s[24:25], 0x30
	s_addc_u32 s5, s5, 0
	s_add_u32 s6, s57, s6
	s_addc_u32 s7, s58, s7
	s_lshl_b32 s33, s83, 1
	v_mbcnt_lo_u32_b32 v229, -1, 0
	v_mbcnt_hi_u32_b32 v229, -1, v229
	s_add_u32 s6, s6, s33
	v_lshrrev_b32_e32 v0, 2, v229
	v_and_b32_e32 v228, 63, v229
	v_and_b32_e32 v227, 31, v229
	v_and_b32_e32 v2, 8, v0
	s_addc_u32 s7, s7, 0
	v_cmp_gt_u32_e32 vcc, 32, v228
	v_mul_u32_u24_e32 v0, 0x600, v227
	v_lshlrev_b32_e32 v168, 1, v0
	v_lshl_add_u64 v[0:1], s[10:11], 0, v[168:169]
	v_lshlrev_b32_e32 v168, 1, v2
	v_lshl_add_u64 v[0:1], v[0:1], 0, v[168:169]
	v_or_b32_e32 v32, s82, v227
	global_load_dwordx4 v[20:23], v[0:1], off
	global_load_dwordx4 v[16:19], v[0:1], off offset:32
	global_load_dwordx4 v[28:31], v[0:1], off offset:64
	global_load_dwordx4 v[24:27], v[0:1], off offset:96
	v_cndmask_b32_e64 v93, v206, 1.0, vcc
	v_ashrrev_i32_e32 v33, 6, v32
	v_cvt_f32_i32_e32 v33, v33
	v_and_b32_e32 v32, 63, v32
	v_cvt_f32_ubyte0_e32 v32, v32
	v_cndmask_b32_e32 v95, v207, v208, vcc
	v_mul_f32_e32 v34, v93, v33
	v_mul_f32_e32 v35, 0.15915494, v34
	v_rndne_f32_e32 v35, v35
	v_fmac_f32_e32 v34, 0xc0c90fdb, v35
	v_fmac_f32_e32 v34, 0x343bbd2e, v35
	v_mul_f32_e32 v34, 0.15915494, v34
	v_sin_f32_e32 v74, v34
	v_cos_f32_e32 v76, v34
	v_mul_f32_e32 v34, v93, v32
	v_mul_f32_e32 v35, 0.15915494, v34
	v_rndne_f32_e32 v35, v35
	v_fmac_f32_e32 v34, 0xc0c90fdb, v35
	v_fmac_f32_e32 v34, 0x343bbd2e, v35
	v_mul_f32_e32 v34, 0.15915494, v34
	v_sin_f32_e32 v78, v34
	v_cos_f32_e32 v80, v34
	v_mul_f32_e32 v34, v95, v33
	v_mul_f32_e32 v35, 0.15915494, v34
	v_rndne_f32_e32 v35, v35
	v_fmac_f32_e32 v34, 0xc0c90fdb, v35
	v_fmac_f32_e32 v34, 0x343bbd2e, v35
	v_mul_f32_e32 v34, 0.15915494, v34
	v_sin_f32_e32 v75, v34
	v_cos_f32_e32 v77, v34
	v_mul_f32_e32 v34, v95, v32
	s_movk_i32 s33, 0x7c
	v_mul_f32_e32 v35, 0.15915494, v34
	v_bitop3_b32 v73, v229, s33, v203 bitop3:0xc8
	s_movk_i32 s33, 0xbc
	v_rndne_f32_e32 v35, v35
	v_lshlrev_b32_e32 v61, 2, v2
	v_bitop3_b32 v69, v229, 60, 28 bitop3:0xc8
	v_bitop3_b32 v92, v229, s33, v204 bitop3:0xc8
	s_movk_i32 s33, 0xfc
	v_fmac_f32_e32 v34, 0xc0c90fdb, v35
	s_waitcnt lgkmcnt(0)
	global_load_dwordx3 v[56:58], v61, s[8:9] offset:16
	global_load_dwordx4 v[12:15], v61, s[8:9]
	global_load_dwordx3 v[52:54], v61, s[8:9] offset:80
	global_load_dwordx4 v[8:11], v61, s[8:9] offset:64
	global_load_dwordx3 v[48:50], v61, s[8:9] offset:144
	global_load_dwordx4 v[4:7], v61, s[8:9] offset:128
	global_load_dwordx3 v[44:46], v61, s[8:9] offset:208
	global_load_dwordx4 v[0:3], v61, s[8:9] offset:192
	v_bitop3_b32 v94, v229, s33, v205 bitop3:0xc8
	global_load_dword v83, v69, s[8:9]
	global_load_dword v55, v73, s[8:9]
	global_load_dword v51, v92, s[8:9]
	global_load_dword v47, v94, s[8:9]
	v_fmac_f32_e32 v34, 0x343bbd2e, v35
	v_mul_f32_e32 v34, 0.15915494, v34
	v_cndmask_b32_e32 v105, v209, v210, vcc
	v_sin_f32_e32 v79, v34
	v_cos_f32_e32 v81, v34
	v_mul_f32_e32 v34, v105, v33
	v_mul_f32_e32 v35, 0.15915494, v34
	v_rndne_f32_e32 v35, v35
	v_fmac_f32_e32 v34, 0xc0c90fdb, v35
	v_fmac_f32_e32 v34, 0x343bbd2e, v35
	v_mul_f32_e32 v34, 0.15915494, v34
	v_sin_f32_e32 v84, v34
	v_cos_f32_e32 v86, v34
	v_mul_f32_e32 v34, v105, v32
	v_mul_f32_e32 v35, 0.15915494, v34
	v_rndne_f32_e32 v35, v35
	v_fmac_f32_e32 v34, 0xc0c90fdb, v35
	v_fmac_f32_e32 v34, 0x343bbd2e, v35
	v_mul_f32_e32 v34, 0.15915494, v34
	v_cndmask_b32_e32 v107, v211, v218, vcc
	v_sin_f32_e32 v88, v34
	v_cos_f32_e32 v90, v34
	v_mul_f32_e32 v34, v107, v33
	v_mul_f32_e32 v35, 0.15915494, v34
	v_rndne_f32_e32 v35, v35
	v_fmac_f32_e32 v34, 0xc0c90fdb, v35
	v_fmac_f32_e32 v34, 0x343bbd2e, v35
	v_mul_f32_e32 v34, 0.15915494, v34
	v_sin_f32_e32 v85, v34
	v_cos_f32_e32 v87, v34
	v_mul_f32_e32 v34, v107, v32
	v_mul_f32_e32 v35, 0.15915494, v34
	v_rndne_f32_e32 v35, v35
	v_fmac_f32_e32 v34, 0xc0c90fdb, v35
	v_fmac_f32_e32 v34, 0x343bbd2e, v35
	v_mul_f32_e32 v34, 0.15915494, v34
	s_waitcnt vmcnt(17)
	v_cndmask_b32_e32 v132, v219, v220, vcc
	v_sin_f32_e32 v89, v34
	v_cos_f32_e32 v91, v34
	v_mul_f32_e32 v34, v132, v33
	v_mul_f32_e32 v35, 0.15915494, v34
	v_rndne_f32_e32 v35, v35
	v_fmac_f32_e32 v34, 0xc0c90fdb, v35
	v_fmac_f32_e32 v34, 0x343bbd2e, v35
	v_mul_f32_e32 v34, 0.15915494, v34
	v_sin_f32_e32 v96, v34
	v_cos_f32_e32 v98, v34
	v_mul_f32_e32 v34, v132, v32
	v_mul_f32_e32 v35, 0.15915494, v34
	v_rndne_f32_e32 v35, v35
	v_fmac_f32_e32 v34, 0xc0c90fdb, v35
	v_fmac_f32_e32 v34, 0x343bbd2e, v35
	v_mul_f32_e32 v34, 0.15915494, v34
	v_cndmask_b32_e32 v134, v221, v222, vcc
	v_sin_f32_e32 v100, v34
	v_cos_f32_e32 v102, v34
	v_mul_f32_e32 v34, v134, v33
	v_mul_f32_e32 v35, 0.15915494, v34
	v_rndne_f32_e32 v35, v35
	v_fmac_f32_e32 v34, 0xc0c90fdb, v35
	v_fmac_f32_e32 v34, 0x343bbd2e, v35
	v_mul_f32_e32 v34, 0.15915494, v34
	v_sin_f32_e32 v97, v34
	v_cos_f32_e32 v99, v34
	v_mul_f32_e32 v34, v134, v32
	v_mul_f32_e32 v35, 0.15915494, v34
	v_rndne_f32_e32 v35, v35
	v_fmac_f32_e32 v34, 0xc0c90fdb, v35
	v_fmac_f32_e32 v34, 0x343bbd2e, v35
	v_mul_f32_e32 v34, 0.15915494, v34
	v_cndmask_b32_e32 v104, v223, v224, vcc
	v_sin_f32_e32 v101, v34
	v_cos_f32_e32 v103, v34
	v_mul_f32_e32 v34, v104, v33
	v_mul_f32_e32 v35, 0.15915494, v34
	v_rndne_f32_e32 v35, v35
	v_fmac_f32_e32 v34, 0xc0c90fdb, v35
	v_fmac_f32_e32 v34, 0x343bbd2e, v35
	v_mul_f32_e32 v34, 0.15915494, v34
	v_sin_f32_e32 v108, v34
	v_cos_f32_e32 v110, v34
	v_mul_f32_e32 v34, v104, v32
	v_mul_f32_e32 v35, 0.15915494, v34
	v_rndne_f32_e32 v35, v35
	v_fmac_f32_e32 v34, 0xc0c90fdb, v35
	v_fmac_f32_e32 v34, 0x343bbd2e, v35
	v_cndmask_b32_e32 v178, v225, v226, vcc
	v_mul_f32_e32 v34, 0.15915494, v34
	v_mul_f32_e32 v33, v178, v33
	s_waitcnt vmcnt(17)
; __device__ __forceinline__ float bflo(unsigned w) { return __uint_as_float(w << 16); }
; __device__ __forceinline__ float bfhi(unsigned w) { return __uint_as_float(w & 0xffff0000u); }
; __device__ __forceinline__ float pairsum(float v) { auto rr = __builtin_amdgcn_permlane32_swap(__float_as_uint(v), __float_as_uint(v), false, false); return __uint_as_float(rr[0]) + __uint_as_float(rr[1]); }
;     ...
;             float v[4][8]; float ss = 0.f;
; #pragma unroll
;             for (int d0 = 0; d0 < 4; ++d0)
; #pragma unroll
;                 for (int j = 0; j < 4; ++j) { const unsigned w = raw[d0][j]; v[d0][2 * j] = bflo(w); v[d0][2 * j + 1] = bfhi(w); ss += v[d0][2 * j] * v[d0][2 * j] + v[d0][2 * j + 1] * v[d0][2 * j + 1]; }
;             ss = pairsum(ss);
;             const float rstd = rsqrtf(ss * (1.0f / 64.0f) + EPSN) * C2_64;
; #pragma unroll
;             for (int d0 = 0; d0 < 4; ++d0)
; #pragma unroll
;                 for (int j = 0; j < 8; ++j) v[d0][j] *= rstd * U.gain[16 * d0 + 8 * hi + j];
;             const int row = pos >> 6, col = pos & 63;
; #pragma unroll
;             for (int j = 0; j < 8; ++j) {
;                 __builtin_amdgcn_sched_barrier(0);
;                 const float fi = hi ? invf_c(8 + j) : invf_c(j); float c, s;
;                 rope_cs(row, fi, c, s); { const float x1 = v[0][j], x2 = v[1][j]; v[0][j] = x1 * c - x2 * s; v[1][j] = x2 * c + x1 * s; }
;                 rope_cs(col, fi, c, s); { const float x1 = v[2][j], x2 = v[3][j]; v[2][j] = x1 * c - x2 * s; v[3][j] = x2 * c + x1 * s; }
;             }
	v_sin_f32_e32 v112, v34
	v_cos_f32_e32 v114, v34
	v_mul_f32_e32 v34, 0.15915494, v33
	v_rndne_f32_e32 v34, v34
	v_fmac_f32_e32 v33, 0xc0c90fdb, v34
	v_fmac_f32_e32 v33, 0x343bbd2e, v34
	v_mul_f32_e32 v33, 0.15915494, v33
	v_mul_f32_e32 v32, v178, v32
	v_sin_f32_e32 v109, v33
	v_cos_f32_e32 v111, v33
	v_mul_f32_e32 v33, 0.15915494, v32
	v_rndne_f32_e32 v33, v33
	v_fmac_f32_e32 v32, 0xc0c90fdb, v33
	v_fmac_f32_e32 v32, 0x343bbd2e, v33
	v_mul_f32_e32 v32, 0.15915494, v32
	s_waitcnt vmcnt(13)
	v_and_b32_e32 v119, 0xffff0000, v31
	v_and_b32_e32 v121, 0xffff0000, v30
	v_sin_f32_e32 v113, v32
	v_cos_f32_e32 v115, v32
	v_lshlrev_b32_e32 v118, 16, v31
	v_lshlrev_b32_e32 v120, 16, v30
	v_mov_b32_e32 v32, v119
	v_mov_b32_e32 v33, v121
	s_waitcnt vmcnt(12)
	v_and_b32_e32 v117, 0xffff0000, v27
	v_mov_b32_e32 v30, v118
	v_mov_b32_e32 v31, v120
	v_pk_mul_f32 v[32:33], v[32:33], v[32:33]
	v_and_b32_e32 v123, 0xffff0000, v26
	v_lshlrev_b32_e32 v116, 16, v27
	v_pk_fma_f32 v[30:31], v[30:31], v[30:31], v[32:33]
	v_lshlrev_b32_e32 v122, 16, v26
	v_mov_b32_e32 v32, v117
	v_mov_b32_e32 v33, v123
	v_mov_b32_e32 v26, v116
	v_mov_b32_e32 v27, v122
	v_pk_mul_f32 v[32:33], v[32:33], v[32:33]
	v_and_b32_e32 v127, 0xffff0000, v29
	v_and_b32_e32 v129, 0xffff0000, v28
	v_pk_fma_f32 v[26:27], v[26:27], v[26:27], v[32:33]
	v_lshlrev_b32_e32 v126, 16, v29
	v_lshlrev_b32_e32 v128, 16, v28
	v_mov_b32_e32 v32, v127
	v_mov_b32_e32 v33, v129
	v_and_b32_e32 v125, 0xffff0000, v25
	v_mov_b32_e32 v28, v126
	v_mov_b32_e32 v29, v128
	v_pk_mul_f32 v[32:33], v[32:33], v[32:33]
	v_and_b32_e32 v131, 0xffff0000, v24
	v_and_b32_e32 v173, 0xffff0000, v21
	v_and_b32_e32 v177, 0xffff0000, v20
	v_lshlrev_b32_e32 v124, 16, v25
	v_pk_fma_f32 v[28:29], v[28:29], v[28:29], v[32:33]
	v_lshlrev_b32_e32 v130, 16, v24
	v_mov_b32_e32 v32, v125
	v_mov_b32_e32 v33, v131
	v_and_b32_e32 v165, 0xffff0000, v22
	v_lshlrev_b32_e32 v172, 16, v21
	v_mul_f32_e32 v36, v173, v173
	v_lshlrev_b32_e32 v176, 16, v20
	v_mul_f32_e32 v20, v177, v177
	v_mov_b32_e32 v24, v124
	v_mov_b32_e32 v25, v130
	v_pk_mul_f32 v[32:33], v[32:33], v[32:33]
	v_and_b32_e32 v161, 0xffff0000, v23
	v_and_b32_e32 v159, 0xffff0000, v19
	v_lshlrev_b32_e32 v164, 16, v22
	v_mul_f32_e32 v22, v165, v165
	v_and_b32_e32 v163, 0xffff0000, v18
	v_pk_fma_f32 v[36:37], v[172:173], v[172:173], v[36:37] op_sel_hi:[1,1,0]
	v_and_b32_e32 v167, 0xffff0000, v17
	v_pk_fma_f32 v[20:21], v[176:177], v[176:177], v[20:21] op_sel_hi:[1,1,0]
	v_and_b32_e32 v175, 0xffff0000, v16
	v_pk_fma_f32 v[24:25], v[24:25], v[24:25], v[32:33]
	v_lshlrev_b32_e32 v160, 16, v23
	v_mul_f32_e32 v32, v161, v161
	v_lshlrev_b32_e32 v158, 16, v19
	v_mul_f32_e32 v34, v159, v159
	v_pk_fma_f32 v[22:23], v[164:165], v[164:165], v[22:23] op_sel_hi:[1,1,0]
	v_lshlrev_b32_e32 v162, 16, v18
	v_mul_f32_e32 v18, v163, v163
	v_lshlrev_b32_e32 v166, 16, v17
	v_mul_f32_e32 v38, v167, v167
	v_lshlrev_b32_e32 v174, 16, v16
	v_mul_f32_e32 v16, v175, v175
	v_pk_add_f32 v[20:21], v[20:21], v[36:37]
	v_pk_fma_f32 v[32:33], v[160:161], v[160:161], v[32:33] op_sel_hi:[1,1,0]
	v_pk_fma_f32 v[34:35], v[158:159], v[158:159], v[34:35] op_sel_hi:[1,1,0]
	s_waitcnt vmcnt(11)
	v_mov_b32_e32 v82, v58
	v_pk_fma_f32 v[18:19], v[162:163], v[162:163], v[18:19] op_sel_hi:[1,1,0]
	v_pk_fma_f32 v[38:39], v[166:167], v[166:167], v[38:39] op_sel_hi:[1,1,0]
	v_pk_fma_f32 v[16:17], v[174:175], v[174:175], v[16:17] op_sel_hi:[1,1,0]
	v_pk_add_f32 v[20:21], v[22:23], v[20:21]
	s_nop 0
	v_pk_add_f32 v[20:21], v[32:33], v[20:21]
	s_nop 0
	v_pk_add_f32 v[16:17], v[16:17], v[20:21]
	s_nop 0
	v_pk_add_f32 v[16:17], v[38:39], v[16:17]
	s_nop 0
	v_pk_add_f32 v[16:17], v[18:19], v[16:17]
	s_nop 0
	v_pk_add_f32 v[16:17], v[34:35], v[16:17]
	s_nop 0
	v_pk_add_f32 v[16:17], v[28:29], v[16:17] op_sel:[1,0] op_sel_hi:[0,1]
	v_pk_add_f32 v[16:17], v[28:29], v[16:17]
	s_nop 0
	v_pk_add_f32 v[16:17], v[30:31], v[16:17] op_sel:[1,0] op_sel_hi:[0,1]
	v_pk_add_f32 v[16:17], v[30:31], v[16:17]
	s_nop 0
	v_pk_add_f32 v[16:17], v[24:25], v[16:17] op_sel:[1,0] op_sel_hi:[0,1]
	v_pk_add_f32 v[16:17], v[24:25], v[16:17]
	s_nop 0
	v_pk_add_f32 v[16:17], v[26:27], v[16:17] op_sel:[1,0] op_sel_hi:[0,1]
	v_pk_add_f32 v[192:193], v[26:27], v[16:17]
	s_nop 0
	v_mov_b32_e32 v65, v192
	s_nop 1
	v_permlane32_swap_b32_e32 v192, v65
	v_or_b32_e32 v18, 32, v228
	v_mul_u32_u24_e32 v16, 0x600, v18
	v_lshlrev_b32_e32 v16, 1, v16
	v_mov_b32_e32 v17, v169
	v_lshl_add_u64 v[16:17], s[10:11], 0, v[16:17]
	v_lshl_add_u64 v[16:17], v[16:17], 0, v[168:169]
	global_load_dwordx4 v[36:39], v[16:17], off
	global_load_dwordx4 v[32:35], v[16:17], off offset:32
	global_load_dwordx4 v[194:197], v[16:17], off offset:64
	global_load_dwordx4 v[40:43], v[16:17], off offset:96
	v_or_b32_e32 v106, s82, v18
	global_load_dwordx3 v[58:60], v61, s[8:9] offset:16
	global_load_dwordx4 v[16:19], v61, s[8:9]
	global_load_dwordx3 v[62:64], v61, s[8:9] offset:80
	global_load_dwordx4 v[20:23], v61, s[8:9] offset:64
	global_load_dwordx3 v[66:68], v61, s[8:9] offset:144
	global_load_dwordx4 v[24:27], v61, s[8:9] offset:128
	global_load_dwordx3 v[70:72], v61, s[8:9] offset:208
	global_load_dwordx4 v[28:31], v61, s[8:9] offset:192
	s_nop 0
	global_load_dword v69, v69, s[8:9]
	s_nop 0
	global_load_dword v61, v73, s[8:9]
	global_load_dword v133, v92, s[8:9]
	s_nop 0
	global_load_dword v73, v94, s[8:9]
	v_and_b32_e32 v92, 63, v106
	v_cvt_f32_ubyte0_e32 v168, v92
	v_mul_f32_e32 v92, v104, v168
	v_mul_f32_e32 v94, 0.15915494, v92
	v_rndne_f32_e32 v94, v94
	v_fmac_f32_e32 v92, 0xc0c90fdb, v94
	v_fmac_f32_e32 v92, 0x343bbd2e, v94
	v_ashrrev_i32_e32 v94, 6, v106
	v_mul_f32_e32 v135, v134, v168
; __device__ __forceinline__ float bflo(unsigned w) { return __uint_as_float(w << 16); }
; __device__ __forceinline__ float bfhi(unsigned w) { return __uint_as_float(w & 0xffff0000u); }
; __device__ __forceinline__ float pairsum(float v) { auto rr = __builtin_amdgcn_permlane32_swap(__float_as_uint(v), __float_as_uint(v), false, false); return __uint_as_float(rr[0]) + __uint_as_float(rr[1]); }
;     ...
;             float v[4][8]; float ss = 0.f;
; #pragma unroll
;             for (int d0 = 0; d0 < 4; ++d0)
; #pragma unroll
;                 for (int j = 0; j < 4; ++j) { const unsigned w = raw[d0][j]; v[d0][2 * j] = bflo(w); v[d0][2 * j + 1] = bfhi(w); ss += v[d0][2 * j] * v[d0][2 * j] + v[d0][2 * j + 1] * v[d0][2 * j + 1]; }
;             ss = pairsum(ss);
;             const float rstd = rsqrtf(ss * (1.0f / 64.0f) + EPSN) * C2_64;
; #pragma unroll
;             for (int d0 = 0; d0 < 4; ++d0)
; #pragma unroll
;                 for (int j = 0; j < 8; ++j) v[d0][j] *= rstd * U.gain[16 * d0 + 8 * hi + j];
;             const int row = pos >> 6, col = pos & 63;
; #pragma unroll
;             for (int j = 0; j < 8; ++j) {
;                 __builtin_amdgcn_sched_barrier(0);
;                 const float fi = hi ? invf_c(8 + j) : invf_c(j); float c, s;
;                 rope_cs(row, fi, c, s); { const float x1 = v[0][j], x2 = v[1][j]; v[0][j] = x1 * c - x2 * s; v[1][j] = x2 * c + x1 * s; }
;                 rope_cs(col, fi, c, s); { const float x1 = v[2][j], x2 = v[3][j]; v[2][j] = x1 * c - x2 * s; v[3][j] = x2 * c + x1 * s; }
;             }
	v_cvt_f32_i32_e32 v179, v94
	v_mul_f32_e32 v136, 0.15915494, v135
	v_rndne_f32_e32 v136, v136
	v_fmac_f32_e32 v135, 0xc0c90fdb, v136
	v_fmac_f32_e32 v135, 0x343bbd2e, v136
	v_mul_f32_e32 v136, 0.15915494, v135
	v_mul_f32_e32 v134, v134, v179
	v_cos_f32_e32 v135, v136
	v_sin_f32_e32 v137, v136
	v_mul_f32_e32 v136, 0.15915494, v134
	v_rndne_f32_e32 v136, v136
	v_fmac_f32_e32 v134, 0xc0c90fdb, v136
	v_fmac_f32_e32 v134, 0x343bbd2e, v136
	v_mul_f32_e32 v134, 0.15915494, v134
	v_cos_f32_e32 v139, v134
	v_sin_f32_e32 v141, v134
	v_mul_f32_e32 v134, v132, v168
	v_mul_f32_e32 v132, v132, v179
	v_mul_f32_e32 v138, 0.15915494, v132
	v_rndne_f32_e32 v138, v138
	v_fmac_f32_e32 v132, 0xc0c90fdb, v138
	v_fmac_f32_e32 v132, 0x343bbd2e, v138
	v_mul_f32_e32 v132, 0.15915494, v132
	v_cos_f32_e32 v138, v132
	v_sin_f32_e32 v140, v132
	v_mul_f32_e32 v132, v107, v168
	v_mul_f32_e32 v142, 0.15915494, v132
	v_rndne_f32_e32 v142, v142
	v_fmac_f32_e32 v132, 0xc0c90fdb, v142
	v_fmac_f32_e32 v132, 0x343bbd2e, v142
	v_mul_f32_e32 v132, 0.15915494, v132
	v_mul_f32_e32 v107, v107, v179
	v_cos_f32_e32 v143, v132
	v_sin_f32_e32 v145, v132
	v_mul_f32_e32 v132, 0.15915494, v107
	v_rndne_f32_e32 v132, v132
	v_fmac_f32_e32 v107, 0xc0c90fdb, v132
	v_fmac_f32_e32 v107, 0x343bbd2e, v132
	v_mul_f32_e32 v107, 0.15915494, v107
	v_cos_f32_e32 v147, v107
	v_sin_f32_e32 v151, v107
	v_mul_f32_e32 v107, v105, v168
	v_mul_f32_e32 v132, 0.15915494, v107
	v_rndne_f32_e32 v132, v132
	v_fmac_f32_e32 v107, 0xc0c90fdb, v132
	v_fmac_f32_e32 v107, 0x343bbd2e, v132
	v_mul_f32_e32 v107, 0.15915494, v107
	v_mul_f32_e32 v105, v105, v179
	v_cos_f32_e32 v142, v107
	v_sin_f32_e32 v144, v107
	v_mul_f32_e32 v107, 0.15915494, v105
	v_rndne_f32_e32 v107, v107
	v_fmac_f32_e32 v105, 0xc0c90fdb, v107
	v_fmac_f32_e32 v105, 0x343bbd2e, v107
	v_mul_f32_e32 v105, 0.15915494, v105
	v_cos_f32_e32 v146, v105
	v_sin_f32_e32 v150, v105
	v_mul_f32_e32 v105, v95, v168
	v_mul_f32_e32 v107, 0.15915494, v105
	v_rndne_f32_e32 v107, v107
	v_fmac_f32_e32 v105, 0xc0c90fdb, v107
	v_fmac_f32_e32 v105, 0x343bbd2e, v107
	v_mul_f32_e32 v105, 0.15915494, v105
	v_mul_f32_e32 v95, v95, v179
	v_cos_f32_e32 v153, v105
	v_sin_f32_e32 v155, v105
	v_mul_f32_e32 v105, 0.15915494, v95
	v_rndne_f32_e32 v105, v105
	v_fmac_f32_e32 v95, 0xc0c90fdb, v105
	v_fmac_f32_e32 v95, 0x343bbd2e, v105
	v_mul_f32_e32 v95, 0.15915494, v95
	v_cos_f32_e32 v149, v95
	v_sin_f32_e32 v157, v95
	v_mul_f32_e32 v95, v93, v168
	v_mul_f32_e32 v105, 0.15915494, v95
	v_rndne_f32_e32 v105, v105
	v_fmac_f32_e32 v95, 0xc0c90fdb, v105
	v_fmac_f32_e32 v95, 0x343bbd2e, v105
	v_mul_f32_e32 v95, 0.15915494, v95
	v_mul_f32_e32 v93, v93, v179
	v_cos_f32_e32 v152, v95
	v_sin_f32_e32 v154, v95
	v_mul_f32_e32 v95, 0.15915494, v93
	v_rndne_f32_e32 v95, v95
	v_fmac_f32_e32 v93, 0xc0c90fdb, v95
	v_fmac_f32_e32 v93, 0x343bbd2e, v95
	v_mul_f32_e32 v93, 0.15915494, v93
	v_cos_f32_e32 v148, v93
	v_sin_f32_e32 v156, v93
	v_mul_f32_e32 v93, v178, v179
	v_mul_f32_e32 v95, 0.15915494, v93
	v_rndne_f32_e32 v95, v95
	v_fmac_f32_e32 v93, 0xc0c90fdb, v95
	v_fmac_f32_e32 v93, 0x343bbd2e, v95
	v_mul_f32_e32 v104, v104, v179
	v_mul_f32_e32 v93, 0.15915494, v93
	s_waitcnt vmcnt(13)
	v_and_b32_e32 v179, 0xffff0000, v197
	v_and_b32_e32 v183, 0xffff0000, v196
	v_sin_f32_e32 v105, v93
	v_cos_f32_e32 v107, v93
	v_mul_f32_e32 v93, v178, v168
	v_lshlrev_b32_e32 v178, 16, v197
	v_lshlrev_b32_e32 v182, 16, v196
	v_mov_b32_e32 v186, v179
	v_mov_b32_e32 v187, v183
	v_mov_b32_e32 v184, v178
	v_mov_b32_e32 v185, v182
	v_pk_mul_f32 v[186:187], v[186:187], v[186:187]
	s_waitcnt vmcnt(12)
	v_and_b32_e32 v181, 0xffff0000, v43
	v_pk_fma_f32 v[230:231], v[184:185], v[184:185], v[186:187]
	v_and_b32_e32 v187, 0xffff0000, v42
	v_lshlrev_b32_e32 v180, 16, v43
	v_lshlrev_b32_e32 v186, 16, v42
	v_mov_b32_e32 v184, v181
	v_mov_b32_e32 v185, v187
	v_mov_b32_e32 v42, v180
	v_mov_b32_e32 v43, v186
	v_pk_mul_f32 v[184:185], v[184:185], v[184:185]
	v_and_b32_e32 v189, 0xffff0000, v41
	v_pk_fma_f32 v[232:233], v[42:43], v[42:43], v[184:185]
	v_and_b32_e32 v185, 0xffff0000, v195
	v_and_b32_e32 v43, 0xffff0000, v194
	v_lshlrev_b32_e32 v184, 16, v195
	v_lshlrev_b32_e32 v42, 16, v194
	v_mov_b32_e32 v194, v185
	v_mov_b32_e32 v195, v43
	v_mov_b32_e32 v190, v184
	v_mov_b32_e32 v191, v42
	v_pk_mul_f32 v[194:195], v[194:195], v[194:195]
	v_lshlrev_b32_e32 v188, 16, v41
	v_pk_fma_f32 v[234:235], v[190:191], v[190:191], v[194:195]
	v_and_b32_e32 v191, 0xffff0000, v40
	v_lshlrev_b32_e32 v190, 16, v40
	v_mov_b32_e32 v194, v189
	v_mov_b32_e32 v195, v191
	v_and_b32_e32 v199, 0xffff0000, v34
	v_mul_f32_e32 v106, 0.15915494, v104
	v_mul_f32_e32 v136, 0.15915494, v134
	v_mov_b32_e32 v40, v188
	v_mov_b32_e32 v41, v190
	v_pk_mul_f32 v[194:195], v[194:195], v[194:195]
	v_and_b32_e32 v197, 0xffff0000, v38
	v_lshlrev_b32_e32 v198, 16, v34
	v_mul_f32_e32 v34, v199, v199
	v_rndne_f32_e32 v106, v106
	v_rndne_f32_e32 v136, v136
	v_pk_fma_f32 v[236:237], v[40:41], v[40:41], v[194:195]
	v_lshlrev_b32_e32 v194, 16, v35
	v_and_b32_e32 v195, 0xffff0000, v35
	v_lshlrev_b32_e32 v196, 16, v38
	v_mul_f32_e32 v38, v197, v197
	v_pk_fma_f32 v[244:245], v[198:199], v[198:199], v[34:35] op_sel_hi:[1,1,0]
	v_and_b32_e32 v35, 0xffff0000, v37
	v_fmac_f32_e32 v104, 0xc0c90fdb, v106
	v_fmac_f32_e32 v134, 0xc0c90fdb, v136
	v_pk_fma_f32 v[242:243], v[196:197], v[196:197], v[38:39] op_sel_hi:[1,1,0]
	v_lshlrev_b32_e32 v34, 16, v37
	v_mul_f32_e32 v38, v35, v35
	v_and_b32_e32 v201, 0xffff0000, v33
	v_fmac_f32_e32 v104, 0x343bbd2e, v106
	v_fmac_f32_e32 v134, 0x343bbd2e, v136
	v_pk_fma_f32 v[246:247], v[34:35], v[34:35], v[38:39] op_sel_hi:[1,1,0]
	v_lshlrev_b32_e32 v200, 16, v33
	v_mul_f32_e32 v38, v201, v201
	v_mul_f32_e32 v104, 0.15915494, v104
	v_mul_f32_e32 v136, 0.15915494, v134
	v_mul_f32_e32 v95, 0.15915494, v93
	v_lshlrev_b32_e32 v40, 16, v39
	v_and_b32_e32 v41, 0xffff0000, v39
	v_pk_fma_f32 v[248:249], v[200:201], v[200:201], v[38:39] op_sel_hi:[1,1,0]
	v_and_b32_e32 v39, 0xffff0000, v36
	v_cos_f32_e32 v106, v104
	v_sin_f32_e32 v104, v104
	v_cos_f32_e32 v134, v136
	v_sin_f32_e32 v136, v136
	v_rndne_f32_e32 v95, v95
	v_lshlrev_b32_e32 v38, 16, v36
	v_mul_f32_e32 v36, v39, v39
	v_fmac_f32_e32 v93, 0xc0c90fdb, v95
	s_waitcnt vmcnt(7)
; __device__ __forceinline__ unsigned pk(float lo, float hi) { f32x2_t v = {lo, hi}; bf16x2_t b = __builtin_convertvector(v, bf16x2_t); return __builtin_bit_cast(unsigned, b); }
; __device__ __forceinline__ float pairsum(float v) { auto rr = __builtin_amdgcn_permlane32_swap(__float_as_uint(v), __float_as_uint(v), false, false); return __uint_as_float(rr[0]) + __uint_as_float(rr[1]); }
;     ...
;             ss = pairsum(ss);
;             const float rstd = rsqrtf(ss * (1.0f / 64.0f) + EPSN) * C2_64;
; #pragma unroll
;             for (int d0 = 0; d0 < 4; ++d0)
; #pragma unroll
;                 for (int j = 0; j < 8; ++j) v[d0][j] *= rstd * U.gain[16 * d0 + 8 * hi + j];
;             const int row = pos >> 6, col = pos & 63;
; #pragma unroll
;             for (int j = 0; j < 8; ++j) {
;                 __builtin_amdgcn_sched_barrier(0);
;                 const float fi = hi ? invf_c(8 + j) : invf_c(j); float c, s;
;                 rope_cs(row, fi, c, s); { const float x1 = v[0][j], x2 = v[1][j]; v[0][j] = x1 * c - x2 * s; v[1][j] = x2 * c + x1 * s; }
;                 rope_cs(col, fi, c, s); { const float x1 = v[2][j], x2 = v[3][j]; v[2][j] = x1 * c - x2 * s; v[3][j] = x2 * c + x1 * s; }
;             }
; #pragma unroll
;             for (int d0 = 0; d0 < 4; ++d0) { u32x4 w; w.x = pk(v[d0][0], v[d0][1]); w.y = pk(v[d0][2], v[d0][3]); w.z = pk(v[d0][4], v[d0][5]); w.w = pk(v[d0][6], v[d0][7]); qf[qb][d0] = __builtin_bit_cast(bf16x8, w); }
	v_mov_b32_e32 v132, v68
	v_mul_f32_e32 v68, v41, v41
	v_pk_fma_f32 v[250:251], v[38:39], v[38:39], v[36:37] op_sel_hi:[1,1,0]
	v_and_b32_e32 v37, 0xffff0000, v32
	v_fmac_f32_e32 v93, 0x343bbd2e, v95
	s_waitcnt vmcnt(3)
	v_pk_fma_f32 v[238:239], v[40:41], v[40:41], v[68:69] op_sel_hi:[1,1,0]
	v_mul_f32_e32 v68, v195, v195
	v_lshlrev_b32_e32 v36, 16, v32
	v_mul_f32_e32 v32, v37, v37
	v_mul_f32_e32 v92, 0.15915494, v92
	v_mul_f32_e32 v95, 0.15915494, v93
	v_pk_fma_f32 v[240:241], v[194:195], v[194:195], v[68:69] op_sel_hi:[1,1,0]
	v_mov_b32_e32 v68, v60
	v_mov_b32_e32 v60, v64
	v_pk_fma_f32 v[32:33], v[36:37], v[36:37], v[32:33] op_sel_hi:[1,1,0]
	v_pk_add_f32 v[246:247], v[250:251], v[246:247]
	v_cos_f32_e32 v94, v92
	v_sin_f32_e32 v92, v92
	v_sin_f32_e32 v93, v95
	v_cos_f32_e32 v95, v95
	v_pk_add_f32 v[242:243], v[242:243], v[246:247]
	s_nop 0
	v_pk_add_f32 v[238:239], v[238:239], v[242:243]
	s_mov_b32 s8, 0x3c800000
	v_pk_add_f32 v[32:33], v[32:33], v[238:239]
	s_mov_b32 s33, 0
	v_pk_add_f32 v[32:33], v[248:249], v[32:33]
	s_nop 0
	v_pk_add_f32 v[32:33], v[244:245], v[32:33]
	s_nop 0
	v_pk_add_f32 v[32:33], v[240:241], v[32:33]
	s_nop 0
	v_pk_add_f32 v[32:33], v[234:235], v[32:33] op_sel:[1,0] op_sel_hi:[0,1]
	v_pk_add_f32 v[32:33], v[234:235], v[32:33]
	s_nop 0
	v_pk_add_f32 v[32:33], v[230:231], v[32:33] op_sel:[1,0] op_sel_hi:[0,1]
	v_pk_add_f32 v[32:33], v[230:231], v[32:33]
	s_nop 0
	v_pk_add_f32 v[32:33], v[236:237], v[32:33] op_sel:[1,0] op_sel_hi:[0,1]
	v_pk_add_f32 v[32:33], v[236:237], v[32:33]
	s_nop 0
	v_pk_add_f32 v[32:33], v[232:233], v[32:33] op_sel:[1,0] op_sel_hi:[0,1]
	v_pk_add_f32 v[32:33], v[232:233], v[32:33]
	s_nop 0
	v_mov_b32_e32 v64, v32
	s_nop 1
	v_permlane32_swap_b32_e32 v32, v64
	v_mov_b32_e32 v33, v192
	v_pk_add_f32 v[32:33], v[32:33], v[64:65]
	s_nop 0
	v_pk_fma_f32 v[32:33], v[32:33], s[8:9], v[170:171] op_sel_hi:[1,0,0]
	s_nop 0
	v_mul_f32_e32 v64, 0x4b800000, v33
	v_cmp_gt_f32_e32 vcc, s71, v33
	s_nop 1
	v_cndmask_b32_e32 v33, v33, v64, vcc
	v_rsq_f32_e32 v33, v33
	s_nop 0
	v_mul_f32_e32 v64, 0x45800000, v33
	v_cndmask_b32_e32 v33, v33, v64, vcc
	v_mul_f32_e32 v64, 0x3e38aa3b, v33
	v_pk_mul_f32 v[8:9], v[8:9], v[64:65] op_sel_hi:[1,0]
	v_pk_mul_f32 v[12:13], v[12:13], v[64:65] op_sel_hi:[1,0]
	v_pk_mul_f32 v[8:9], v[8:9], v[174:175]
	v_pk_mul_f32 v[12:13], v[12:13], v[176:177]
	v_pk_mul_f32 v[14:15], v[14:15], v[64:65] op_sel_hi:[1,0]
	v_pk_mul_f32 v[56:57], v[56:57], v[64:65] op_sel_hi:[1,0]
	v_pk_mul_f32 v[82:83], v[82:83], v[64:65] op_sel_hi:[1,0]
	v_pk_mul_f32 v[10:11], v[64:65], v[10:11] op_sel_hi:[0,1]
	v_pk_mul_f32 v[52:53], v[64:65], v[52:53] op_sel_hi:[0,1]
	v_pk_mul_f32 v[54:55], v[64:65], v[54:55] op_sel_hi:[0,1]
	v_pk_mul_f32 v[4:5], v[64:65], v[4:5] op_sel_hi:[0,1]
	v_pk_mul_f32 v[6:7], v[64:65], v[6:7] op_sel_hi:[0,1]
	v_pk_mul_f32 v[48:49], v[64:65], v[48:49] op_sel_hi:[0,1]
	v_pk_mul_f32 v[50:51], v[64:65], v[50:51] op_sel_hi:[0,1]
	v_pk_mul_f32 v[0:1], v[64:65], v[0:1] op_sel_hi:[0,1]
	v_pk_mul_f32 v[2:3], v[64:65], v[2:3] op_sel_hi:[0,1]
	v_pk_mul_f32 v[44:45], v[64:65], v[44:45] op_sel_hi:[0,1]
	v_pk_mul_f32 v[46:47], v[64:65], v[46:47] op_sel_hi:[0,1]
	v_pk_mul_f32 v[64:65], v[74:75], v[8:9]
	v_pk_mul_f32 v[0:1], v[0:1], v[130:131]
	v_pk_fma_f32 v[64:65], v[76:77], v[12:13], v[64:65] neg_lo:[0,0,1] neg_hi:[0,0,1]
	v_pk_mul_f32 v[12:13], v[74:75], v[12:13]
	v_pk_mul_f32 v[10:11], v[10:11], v[166:167]
	v_pk_mul_f32 v[4:5], v[4:5], v[128:129]
	v_pk_fma_f32 v[8:9], v[76:77], v[8:9], v[12:13]
	v_pk_mul_f32 v[12:13], v[78:79], v[0:1]
	v_pk_mul_f32 v[0:1], v[80:81], v[0:1]
	v_pk_mul_f32 v[14:15], v[14:15], v[172:173]
	v_pk_mul_f32 v[2:3], v[2:3], v[124:125]
	v_pk_fma_f32 v[74:75], v[80:81], v[4:5], v[12:13] neg_lo:[0,0,1] neg_hi:[0,0,1]
	v_pk_fma_f32 v[76:77], v[78:79], v[4:5], v[0:1]
	v_pk_mul_f32 v[4:5], v[86:87], v[10:11]
	v_pk_mul_f32 v[52:53], v[52:53], v[162:163]
	v_pk_mul_f32 v[6:7], v[6:7], v[126:127]
	v_pk_mul_f32 v[0:1], v[84:85], v[10:11]
	v_pk_fma_f32 v[78:79], v[84:85], v[14:15], v[4:5]
	v_pk_mul_f32 v[4:5], v[88:89], v[2:3]
	v_pk_mul_f32 v[56:57], v[56:57], v[164:165]
	v_pk_mul_f32 v[44:45], v[44:45], v[122:123]
	v_pk_fma_f32 v[0:1], v[86:87], v[14:15], v[0:1] neg_lo:[0,0,1] neg_hi:[0,0,1]
	v_pk_fma_f32 v[80:81], v[90:91], v[6:7], v[4:5] neg_lo:[0,0,1] neg_hi:[0,0,1]
	v_pk_mul_f32 v[2:3], v[90:91], v[2:3]
	v_pk_mul_f32 v[4:5], v[98:99], v[52:53]
	v_pk_mul_f32 v[54:55], v[54:55], v[158:159]
	v_pk_mul_f32 v[48:49], v[48:49], v[120:121]
	v_pk_mul_f32 v[46:47], v[46:47], v[116:117]
	v_pk_fma_f32 v[84:85], v[88:89], v[6:7], v[2:3]
	v_pk_mul_f32 v[2:3], v[96:97], v[52:53]
	v_pk_fma_f32 v[52:53], v[96:97], v[56:57], v[4:5]
	v_pk_mul_f32 v[4:5], v[100:101], v[44:45]
	v_cvt_pk_bf16_f32 v117, v0, v1
	v_add_u32_e32 v0, s36, v229
	v_lshlrev_b32_e32 v1, 4, v229
	v_pk_mul_f32 v[82:83], v[82:83], v[160:161]
	v_pk_fma_f32 v[2:3], v[98:99], v[56:57], v[2:3] neg_lo:[0,0,1] neg_hi:[0,0,1]
	v_pk_fma_f32 v[56:57], v[102:103], v[48:49], v[4:5] neg_lo:[0,0,1] neg_hi:[0,0,1]
	v_pk_mul_f32 v[4:5], v[102:103], v[44:45]
	v_pk_mul_f32 v[6:7], v[110:111], v[54:55]
	v_ashrrev_i32_e32 v33, 3, v0
	v_and_b32_e32 v86, 0x70, v1
	v_pk_mul_f32 v[50:51], v[50:51], v[118:119]
	v_pk_fma_f32 v[44:45], v[100:101], v[48:49], v[4:5]
	v_pk_fma_f32 v[48:49], v[108:109], v[82:83], v[6:7]
	v_pk_mul_f32 v[6:7], v[112:113], v[46:47]
	v_lshl_or_b32 v168, v33, 8, v86
	v_pk_mul_f32 v[4:5], v[108:109], v[54:55]
	v_pk_fma_f32 v[54:55], v[114:115], v[50:51], v[6:7] neg_lo:[0,0,1] neg_hi:[0,0,1]
	v_pk_mul_f32 v[6:7], v[114:115], v[46:47]
	v_cvt_pk_bf16_f32 v116, v64, v65
	v_lshl_add_u64 v[64:65], s[4:5], 0, v[168:169]
; __device__ __forceinline__ unsigned pk(float lo, float hi) { f32x2_t v = {lo, hi}; bf16x2_t b = __builtin_convertvector(v, bf16x2_t); return __builtin_bit_cast(unsigned, b); }
; #define BAR_LDS() asm volatile("s_waitcnt lgkmcnt(0)\n\ts_barrier" ::: "memory")
; #define ATT_LOADS(RK, RR, RV, tt) do { RK = *(const u32x4*)((const char*)(U.k + (size_t)(tt) * 64 * KP) + kgo); if (MODE == 2) RR = *(const u32x2*)((const char*)(U.kr + (size_t)(tt) * 64 * 32) + krgo); \
;         RV = *(const u32x4*)((const char*)(U.vt + (size_t)(tt) * VTS) + vgo); } while (0)
; #define ATT_LOAD(tt) ATT_LOADS(rk, rr, rv, tt)
; #define ATT_STORE(ss) ATT_STORES(rk, rr, rv, ss)
;     ...
;             const float rstd = rsqrtf(ss * (1.0f / 64.0f) + EPSN) * C2_64;
; #pragma unroll
;             for (int d0 = 0; d0 < 4; ++d0)
; #pragma unroll
;                 for (int j = 0; j < 8; ++j) v[d0][j] *= rstd * U.gain[16 * d0 + 8 * hi + j];
;             const int row = pos >> 6, col = pos & 63;
; #pragma unroll
;             for (int j = 0; j < 8; ++j) {
;                 __builtin_amdgcn_sched_barrier(0);
;                 const float fi = hi ? invf_c(8 + j) : invf_c(j); float c, s;
;                 rope_cs(row, fi, c, s); { const float x1 = v[0][j], x2 = v[1][j]; v[0][j] = x1 * c - x2 * s; v[1][j] = x2 * c + x1 * s; }
;                 rope_cs(col, fi, c, s); { const float x1 = v[2][j], x2 = v[3][j]; v[2][j] = x1 * c - x2 * s; v[3][j] = x2 * c + x1 * s; }
;             }
; #pragma unroll
;             for (int d0 = 0; d0 < 4; ++d0) { u32x4 w; w.x = pk(v[d0][0], v[d0][1]); w.y = pk(v[d0][2], v[d0][3]); w.z = pk(v[d0][4], v[d0][5]); w.w = pk(v[d0][6], v[d0][7]); qf[qb][d0] = __builtin_bit_cast(bf16x8, w); }
; template <int MODE, bool FAST> __device__ __forceinline__ bool attn_unit(LAS unsigned char* lds, const AttU& U, const int wv) {
;     ...
;     const int NT = U.kt1 - U.kt0;
;     ATT_LOAD(U.kt0); ATT_STORE(0);
;     if (NT > 1) { ATT_LOAD(U.kt0 + 1); ATT_STORE(1); }
;     if (NT > 2) ATT_LOAD(U.kt0 + 2);
;     if constexpr (FAST) { if (NT > 3) ATT_LOADS(rk2, rr2, rv2, U.kt0 + 3); }
;     BAR_LDS();
	v_pk_fma_f32 v[46:47], v[112:113], v[50:51], v[6:7]
	v_cvt_pk_bf16_f32 v120, v8, v9
	v_lshlrev_b32_e32 v50, 4, v0
	v_mov_b32_e32 v51, v169
	v_add_co_u32_e32 v8, vcc, s72, v64
	v_pk_fma_f32 v[4:5], v[110:111], v[82:83], v[4:5] neg_lo:[0,0,1] neg_hi:[0,0,1]
	v_lshl_add_u64 v[82:83], s[6:7], 0, v[50:51]
	v_addc_co_u32_e32 v9, vcc, 0, v65, vcc
	v_add_co_u32_e32 v12, vcc, s72, v82
	v_cvt_pk_bf16_f32 v118, v2, v3
	s_nop 0
	v_addc_co_u32_e32 v13, vcc, 0, v83, vcc
	v_cvt_pk_bf16_f32 v119, v4, v5
	global_load_dwordx4 v[0:3], v168, s[4:5]
	global_load_dwordx4 v[4:7], v50, s[6:7]
	s_nop 0
	global_load_dwordx4 v[8:11], v[8:9], off
	s_nop 0
	global_load_dwordx4 v[12:15], v[12:13], off
	v_cvt_pk_bf16_f32 v123, v48, v49
	v_mul_f32_e32 v48, 0x4b800000, v32
	v_cmp_gt_f32_e32 vcc, s71, v32
	v_cvt_pk_bf16_f32 v130, v44, v45
	v_cvt_pk_bf16_f32 v122, v52, v53
	v_cndmask_b32_e32 v32, v32, v48, vcc
	v_rsq_f32_e32 v32, v32
	v_cvt_pk_bf16_f32 v126, v56, v57
	v_cvt_pk_bf16_f32 v127, v54, v55
	v_cvt_pk_bf16_f32 v131, v46, v47
	v_mul_f32_e32 v44, 0x45800000, v32
	v_cndmask_b32_e32 v32, v32, v44, vcc
	v_mul_f32_e32 v32, 0x3e38aa3b, v32
	v_pk_mul_f32 v[30:31], v[32:33], v[30:31] op_sel_hi:[0,1]
	v_pk_mul_f32 v[26:27], v[32:33], v[26:27] op_sel_hi:[0,1]
	v_pk_mul_f32 v[30:31], v[30:31], v[188:189]
	v_pk_mul_f32 v[18:19], v[18:19], v[32:33] op_sel_hi:[1,0]
	v_pk_mul_f32 v[22:23], v[32:33], v[22:23] op_sel_hi:[0,1]
	v_pk_mul_f32 v[26:27], v[26:27], v[184:185]
	v_pk_mul_f32 v[18:19], v[18:19], v[34:35]
	v_pk_mul_f32 v[22:23], v[22:23], v[200:201]
	v_pk_mul_f32 v[34:35], v[142:143], v[30:31]
	v_pk_mul_f32 v[30:31], v[144:145], v[30:31]
	v_pk_mul_f32 v[48:49], v[68:69], v[32:33] op_sel_hi:[1,0]
	v_pk_fma_f32 v[34:35], v[144:145], v[26:27], v[34:35]
	v_pk_fma_f32 v[26:27], v[142:143], v[26:27], v[30:31] neg_lo:[0,0,1] neg_hi:[0,0,1]
	v_pk_mul_f32 v[30:31], v[146:147], v[22:23]
	v_pk_mul_f32 v[22:23], v[150:151], v[22:23]
	s_waitcnt vmcnt(5)
	v_pk_mul_f32 v[44:45], v[32:33], v[132:133] op_sel_hi:[0,1]
	s_waitcnt vmcnt(4)
	v_pk_mul_f32 v[46:47], v[32:33], v[72:73] op_sel_hi:[0,1]
	v_pk_mul_f32 v[40:41], v[48:49], v[40:41]
	v_pk_mul_f32 v[48:49], v[32:33], v[60:61] op_sel_hi:[0,1]
	v_pk_mul_f32 v[52:53], v[32:33], v[66:67] op_sel_hi:[0,1]
	v_pk_mul_f32 v[54:55], v[32:33], v[70:71] op_sel_hi:[0,1]
	v_pk_mul_f32 v[56:57], v[58:59], v[32:33] op_sel_hi:[1,0]
	v_pk_mul_f32 v[58:59], v[32:33], v[62:63] op_sel_hi:[0,1]
	v_pk_fma_f32 v[30:31], v[150:151], v[18:19], v[30:31]
	v_pk_fma_f32 v[18:19], v[146:147], v[18:19], v[22:23] neg_lo:[0,0,1] neg_hi:[0,0,1]
	v_pk_mul_f32 v[22:23], v[32:33], v[24:25] op_sel_hi:[0,1]
	v_pk_mul_f32 v[24:25], v[32:33], v[28:29] op_sel_hi:[0,1]
	v_pk_mul_f32 v[16:17], v[16:17], v[32:33] op_sel_hi:[1,0]
	v_pk_mul_f32 v[20:21], v[20:21], v[32:33] op_sel_hi:[1,0]
	v_mul_lo_u32 v33, v33, s60
	v_add3_u32 v173, v33, v86, 0
	s_waitcnt vmcnt(3)
	ds_write_b128 v173, v[0:3]
	s_waitcnt vmcnt(2)
	ds_write_b128 v173, v[4:7] offset:9216
	s_waitcnt vmcnt(1)
	ds_write_b128 v173, v[8:11] offset:18432
	s_waitcnt vmcnt(0)
	ds_write_b128 v173, v[12:15] offset:27648
	v_add_co_u32_e32 v0, vcc, s73, v64
	v_pk_mul_f32 v[54:55], v[54:55], v[186:187]
	s_nop 0
	v_addc_co_u32_e32 v1, vcc, 0, v65, vcc
	v_pk_mul_f32 v[52:53], v[52:53], v[182:183]
	v_pk_mul_f32 v[58:59], v[58:59], v[198:199]
	v_pk_mul_f32 v[60:61], v[134:135], v[54:55]
	v_pk_mul_f32 v[54:55], v[136:137], v[54:55]
	v_add_co_u32_e32 v2, vcc, s73, v82
	v_pk_mul_f32 v[56:57], v[56:57], v[196:197]
	v_pk_fma_f32 v[60:61], v[136:137], v[52:53], v[60:61]
	v_pk_fma_f32 v[52:53], v[134:135], v[52:53], v[54:55] neg_lo:[0,0,1] neg_hi:[0,0,1]
	v_pk_mul_f32 v[54:55], v[138:139], v[58:59]
	v_pk_mul_f32 v[58:59], v[140:141], v[58:59]
	v_addc_co_u32_e32 v3, vcc, 0, v83, vcc
	v_pk_fma_f32 v[54:55], v[140:141], v[56:57], v[54:55]
	v_pk_fma_f32 v[56:57], v[138:139], v[56:57], v[58:59] neg_lo:[0,0,1] neg_hi:[0,0,1]
	global_load_dwordx4 v[132:135], v[0:1], off
	global_load_dwordx4 v[136:139], v[2:3], off
	v_add_co_u32_e32 v0, vcc, s74, v64
	v_bfe_u32 v32, v229, 5, 1
	s_nop 0
	v_addc_co_u32_e32 v1, vcc, 0, v65, vcc
	v_add_co_u32_e32 v2, vcc, s74, v82
	v_lshlrev_b32_e32 v172, 4, v32
	s_nop 0
	v_addc_co_u32_e32 v3, vcc, 0, v83, vcc
	global_load_dwordx4 v[140:143], v[0:1], off
	global_load_dwordx4 v[144:147], v[2:3], off
	v_mul_u32_u24_e32 v0, 0x90, v227
	s_waitcnt lgkmcnt(0)
	s_barrier
; #define LAS __attribute__((address_space(3)))
; template <int MODE, bool FAST> __device__ __forceinline__ bool attn_unit(LAS unsigned char* lds, const AttU& U, const int wv) {
;     ...
;     const unsigned koff = r32 * KSTR + hi * 16, voff = 64 * KSTR + r32 * VSTR + hi * 16;
;     ...
;     pb[1][0] = (bf16x8){0, 0, 0, 0, 0, 0, 0, 0}; pb[1][1] = pb[1][0];
;     ATT_QK(0, 0, 0);
;     bf16x8 kpre[NPRE > 0 ? NPRE : 1];
; #pragma unroll
;     for (int i_ = 0; i_ < NPRE; ++i_) kpre[i_] = *(LAS const bf16x8*)(lds + koff + i_ * 32);
;     ...
;     if constexpr (FAST) {
;         for (int t2 = U.kt0; t2 < U.kt1; t2 += 2) { ATT_TILE(t2, 4, rk, rr, rv); ATT_TILE(t2 + 1, 4, rk2, rr2, rv2); }
	v_add3_u32 v184, v172, v0, 0
	v_cvt_pk_bf16_f32 v125, v80, v81
	ds_read_b128 v[80:83], v184
	ds_read_b128 v[108:111], v184 offset:32
	v_cvt_pk_bf16_f32 v121, v78, v79
	v_cvt_pk_bf16_f32 v124, v74, v75
	v_cvt_pk_bf16_f32 v128, v76, v77
	s_waitcnt lgkmcnt(1)
	v_mfma_f32_32x32x16_bf16 v[64:79], v[80:83], v[116:119], 0
	v_mul_f32_e64 v48, v48, v194
	v_mul_f32_e64 v49, v49, v195
	v_mul_f32_e64 v24, v24, v190
	v_mul_f32_e64 v25, v25, v191
	v_mul_f32_e64 v2, v104, v48
	v_mul_f32_e64 v3, v105, v49
	v_pk_mul_f32 v[4:5], v[106:107], v[48:49]
	v_pk_fma_f32 v[2:3], v[106:107], v[40:41], v[2:3] neg_lo:[0,0,1] neg_hi:[0,0,1]
	v_pk_fma_f32 v[4:5], v[104:105], v[40:41], v[4:5]
	ds_read_b128 v[104:107], v184 offset:64
	s_waitcnt lgkmcnt(1)
	v_mfma_f32_32x32x16_bf16 v[64:79], v[108:111], v[120:123], v[64:79]
	v_mul_f32_e64 v22, v22, v42
	v_mul_f32_e64 v23, v23, v43
	v_mul_f32_e64 v16, v16, v38
	v_mul_f32_e64 v17, v17, v39
	v_mul_f32_e64 v28, v152, v24
	v_mul_f32_e64 v29, v153, v25
	v_pk_mul_f32 v[24:25], v[154:155], v[24:25]
	v_pk_mul_f32 v[20:21], v[20:21], v[36:37]
	v_pk_fma_f32 v[28:29], v[154:155], v[22:23], v[28:29]
	v_pk_fma_f32 v[22:23], v[152:153], v[22:23], v[24:25] neg_lo:[0,0,1] neg_hi:[0,0,1]
	v_pk_mul_f32 v[24:25], v[156:157], v[16:17]
	v_cvt_pk_bf16_f32 v151, v2, v3
	v_pk_fma_f32 v[24:25], v[148:149], v[20:21], v[24:25]
	v_pk_mul_f32 v[20:21], v[156:157], v[20:21]
	v_cvt_pk_bf16_f32 v129, v84, v85
	v_pk_fma_f32 v[0:1], v[148:149], v[16:17], v[20:21] neg_lo:[0,0,1] neg_hi:[0,0,1]
	v_pk_mul_f32 v[46:47], v[46:47], v[180:181]
	v_cvt_pk_bf16_f32 v148, v0, v1
	ds_read_b128 v[0:3], v184 offset:96
	s_waitcnt lgkmcnt(1)
	v_mfma_f32_32x32x16_bf16 v[64:79], v[104:107], v[124:127], v[64:79]
	v_mul_f32_e64 v44, v44, v178
	v_mul_f32_e64 v45, v45, v179
	v_mul_f32_e64 v6, v92, v46
	v_mul_f32_e64 v7, v93, v47
	v_mul_f32_e64 v8, v94, v46
	v_mul_f32_e64 v9, v95, v47
	v_pk_fma_f32 v[6:7], v[94:95], v[44:45], v[6:7] neg_lo:[0,0,1] neg_hi:[0,0,1]
	v_pk_fma_f32 v[8:9], v[92:93], v[44:45], v[8:9]
	v_mov_b32_e32 v48, 0
	v_cvt_pk_bf16_f32 v149, v18, v19
	s_waitcnt lgkmcnt(0)
	v_mfma_f32_32x32x16_bf16 v[64:79], v[0:3], v[128:131], v[64:79]
	v_cvt_pk_bf16_f32 v150, v56, v57
	v_cvt_pk_bf16_f32 v152, v24, v25
	v_cvt_pk_bf16_f32 v153, v30, v31
	v_cvt_pk_bf16_f32 v154, v54, v55
	v_cvt_pk_bf16_f32 v155, v4, v5
	v_cvt_pk_bf16_f32 v156, v22, v23
	v_cvt_pk_bf16_f32 v157, v26, v27
	v_cvt_pk_bf16_f32 v158, v52, v53
	v_cvt_pk_bf16_f32 v159, v6, v7
	v_cvt_pk_bf16_f32 v160, v28, v29
	v_cvt_pk_bf16_f32 v161, v34, v35
	v_cvt_pk_bf16_f32 v162, v60, v61
	v_cvt_pk_bf16_f32 v163, v8, v9
	v_mov_b32_e32 v174, v168
	v_mov_b32_e32 v176, v50
	s_add_u32 s98, s46, s14
	s_addc_u32 s99, s47, s15
	s_add_u32 s98, s98, 0x12310000
	s_addc_u32 s99, s99, 0
	s_add_u32 s100, s46, s42
	s_addc_u32 s101, s47, s43
	s_add_u32 s100, s100, 0x12f10000
	s_addc_u32 s101, s101, 0
	s_mov_b64 s[42:43], 0
	v_mov_b32_e32 v96, 0
	v_mov_b32_e32 v97, 0
	v_mov_b32_e32 v98, 0
	v_mov_b32_e32 v99, 0
	v_mov_b32_e32 v100, 0
	v_mov_b32_e32 v101, 0
	v_mov_b32_e32 v102, 0
	v_mov_b32_e32 v103, 0
	v_mov_b32_e32 v49, v48
	v_mov_b32_e32 v50, v48
	v_mov_b32_e32 v51, v48
	v_mov_b32_e32 v52, v48
	v_mov_b32_e32 v53, v48
	v_mov_b32_e32 v54, v48
	v_mov_b32_e32 v55, v48
	v_mov_b32_e32 v56, v48
	v_mov_b32_e32 v57, v48
	v_mov_b32_e32 v58, v48
	v_mov_b32_e32 v59, v48
	v_mov_b32_e32 v60, v48
	v_mov_b32_e32 v61, v48
	v_mov_b32_e32 v62, v48
	v_mov_b32_e32 v63, v48
	v_mov_b32_e32 v32, v48
	v_mov_b32_e32 v33, v48
	v_mov_b32_e32 v34, v48
	v_mov_b32_e32 v35, v48
	v_mov_b32_e32 v36, v48
	v_mov_b32_e32 v37, v48
	v_mov_b32_e32 v38, v48
	v_mov_b32_e32 v39, v48
	v_mov_b32_e32 v40, v48
	v_mov_b32_e32 v41, v48
	v_mov_b32_e32 v42, v48
	v_mov_b32_e32 v43, v48
	v_mov_b32_e32 v44, v48
	v_mov_b32_e32 v45, v48
	v_mov_b32_e32 v46, v48
	v_mov_b32_e32 v47, v48
	v_mov_b32_e32 v16, v48
	v_mov_b32_e32 v17, v48
	v_mov_b32_e32 v18, v48
	v_mov_b32_e32 v19, v48
	v_mov_b32_e32 v20, v48
	v_mov_b32_e32 v21, v48
	v_mov_b32_e32 v22, v48
	v_mov_b32_e32 v23, v48
	v_mov_b32_e32 v24, v48
	v_mov_b32_e32 v25, v48
	v_mov_b32_e32 v26, v48
	v_mov_b32_e32 v27, v48
	v_mov_b32_e32 v28, v48
	v_mov_b32_e32 v29, v48
	v_mov_b32_e32 v30, v48
	v_mov_b32_e32 v31, v48
	v_mov_b32_e32 v0, v48
	v_mov_b32_e32 v1, v48
	v_mov_b32_e32 v2, v48
	v_mov_b32_e32 v3, v48
	v_mov_b32_e32 v4, v48
	v_mov_b32_e32 v5, v48
	v_mov_b32_e32 v6, v48
	v_mov_b32_e32 v7, v48
	v_mov_b32_e32 v8, v48
	v_mov_b32_e32 v9, v48
	v_mov_b32_e32 v10, v48
	v_mov_b32_e32 v11, v48
	v_mov_b32_e32 v12, v48
	v_mov_b32_e32 v13, v48
	v_mov_b32_e32 v14, v48
	v_mov_b32_e32 v15, v48
	v_mov_b32_e32 v178, v48
	v_mov_b32_e32 v179, v48
	s_bitcmp1_b32 s36, 8
	s_cbranch_scc0 .Lprio_dense
	s_setprio 1
.Lprio_dense:
.LBB0_437:
	s_add_i32 s14, s33, 2
	s_cmpk_gt_u32 s33, 0xfd
	s_cselect_b64 s[44:45], -1, 0
	s_and_b64 vcc, exec, s[44:45]
	s_cbranch_vccnz .LBB0_439
	s_and_b32 s4, s14, 2
	s_mulk_i32 s4, 0x4800
	v_add_u32_e32 v84, s4, v173
	s_waitcnt vmcnt(1)
	ds_write_b128 v84, v[132:135]
	s_waitcnt vmcnt(0)
	ds_write_b128 v84, v[136:139] offset:9216

; #define LAS __attribute__((address_space(3)))
; __device__ __forceinline__ unsigned pk(float lo, float hi) { f32x2_t v = {lo, hi}; bf16x2_t b = __builtin_convertvector(v, bf16x2_t); return __builtin_bit_cast(unsigned, b); }
; __device__ __forceinline__ float pairsum(float v) { auto rr = __builtin_amdgcn_permlane32_swap(__float_as_uint(v), __float_as_uint(v), false, false); return __uint_as_float(rr[0]) + __uint_as_float(rr[1]); }
; #define BAR_LDS() asm volatile("s_waitcnt lgkmcnt(0)\n\ts_barrier" ::: "memory")
; #define ATT_PV(Y, sp, kh) do { LAS const unsigned char* vp_ = lds + (sp) * STG + voff + (kh) * 64; \
;         _Pragma("unroll") for (int db = 0; db < 2; ++db) _Pragma("unroll") for (int ks = 0; ks < 2; ++ks) \
;             o[Y][db] = MFMA32(*(LAS const bf16x8*)(vp_ + db * 32 * VSTR + ks * 32), pb[Y][ks], o[Y][db]); } while (0)
; template <int MODE, bool FAST> __device__ __forceinline__ bool attn_unit(LAS unsigned char* lds, const AttU& U, const int wv) {
;     ...
;     ATT_PV(1, (NT - 1) & 3, 1);
;     BAR_LDS();
;     ...
;     if constexpr (FAST) {
;         volatile LAS unsigned* vote = (volatile LAS unsigned*)(lds + 131072 + 64);
;         if (lane == 0) vote[wv] = bad_ ? 1u : 0u;
;         BAR_LDS();
;         const unsigned any_ = vote[0] | vote[1] | vote[2] | vote[3] | vote[4] | vote[5] | vote[6] | vote[7];
;         BAR_LDS();
;         if (any_) return true;
;     }
; #pragma unroll
;     for (int qb = 0; qb < 2; ++qb) {
;         const float inv = 1.0f / pairsum(lsum[qb]);
;         bf16_t* op = U.o + (size_t)(32 * qb + r32) * DM + 8 * hi;
; #pragma unroll
;         for (int db = 0; db < 2; ++db)
; #pragma unroll
;             for (int k = 0; k < 2; ++k) {
;                 const int ga = 2 * k, gb = 2 * k + 1;
;                 const unsigned ax = pk(o[qb][db][4 * ga] * inv, o[qb][db][4 * ga + 1] * inv), ay = pk(o[qb][db][4 * ga + 2] * inv, o[qb][db][4 * ga + 3] * inv);
;                 const unsigned bx = pk(o[qb][db][4 * gb] * inv, o[qb][db][4 * gb + 1] * inv), by = pk(o[qb][db][4 * gb + 2] * inv, o[qb][db][4 * gb + 3] * inv);
;                 auto rx = __builtin_amdgcn_permlane32_swap(ax, bx, false, false); auto ry = __builtin_amdgcn_permlane32_swap(ay, by, false, false);
;                 u32x4 w; w.x = rx[0]; w.y = ry[0]; w.z = rx[1]; w.w = ry[1];
;                 *(u32x4*)(op + 32 * db + 16 * k) = w; }
;     }
.LBB0_451:
	s_setprio 0
	ds_read_b128 v[64:67], v184 offset:64576
	ds_read_b128 v[68:71], v184 offset:64608
	v_add_u32_e32 v72, 0xfc00, v184
	v_cmp_eq_u32_e32 vcc, 0, v228
	s_waitcnt lgkmcnt(1)
	v_mfma_f32_32x32x16_bf16 v[16:31], v[64:67], v[96:99], v[16:31]
	s_waitcnt lgkmcnt(0)
	v_mfma_f32_32x32x16_bf16 v[16:31], v[68:71], v[100:103], v[16:31]
	ds_read_b128 v[64:67], v72 offset:4672
	ds_read_b128 v[68:71], v72 offset:4704
	s_waitcnt lgkmcnt(0)
	s_barrier
	s_waitcnt lgkmcnt(1)
	v_mfma_f32_32x32x16_bf16 v[0:15], v[64:67], v[96:99], v[0:15]
	s_waitcnt lgkmcnt(0)
	v_mfma_f32_32x32x16_bf16 v[0:15], v[68:71], v[100:103], v[0:15]
	s_and_saveexec_b64 s[4:5], vcc
	v_cndmask_b32_e64 v64, 0, 1, s[42:43]
	v_mov_b32_e32 v65, s96
	ds_write_b32 v65, v64
	s_or_b64 exec, exec, s[4:5]
	s_add_i32 s4, 0, 0x20040
	s_waitcnt lgkmcnt(0)
	s_barrier
	v_mov_b32_e32 v64, s4
	v_mov_b32_e32 v65, s63
	ds_read_b32 v64, v64
	ds_read_b32 v65, v65
	v_mov_b32_e32 v66, s64
	ds_read_b32 v66, v66
	v_mov_b32_e32 v67, s67
	v_mov_b32_e32 v68, s68
	s_waitcnt lgkmcnt(1)
	v_or_b32_e32 v64, v65, v64
	v_mov_b32_e32 v65, s65
	s_waitcnt lgkmcnt(0)
	v_or_b32_e32 v64, v64, v66
	ds_read_b32 v65, v65
	v_mov_b32_e32 v66, s66
	ds_read_b32 v66, v66
	ds_read_b32 v67, v67
	ds_read_b32 v68, v68
	v_mov_b32_e32 v69, s69
	ds_read_b32 v69, v69
	s_waitcnt lgkmcnt(4)
	v_or_b32_e32 v64, v64, v65
	s_waitcnt lgkmcnt(3)
	v_or_b32_e32 v64, v64, v66
	s_waitcnt lgkmcnt(2)
	v_or_b32_e32 v64, v64, v67
	s_waitcnt lgkmcnt(1)
	v_or_b32_e32 v64, v64, v68
	s_waitcnt lgkmcnt(0)
	v_or_b32_e32 v64, v64, v69
	s_waitcnt lgkmcnt(0)
	s_barrier
	v_cmp_ne_u32_e32 vcc, 0, v64
	s_cbranch_vccnz .LBB0_456
	v_mov_b32_e32 v64, v178
	s_nop 1
	v_permlane32_swap_b32_e32 v178, v64
	v_add_f32_e32 v64, v178, v64
	v_div_scale_f32 v65, s[4:5], v64, v64, 1.0
	v_rcp_f32_e32 v66, v65
	v_lshlrev_b32_e32 v168, 11, v227
	v_mov_b32_e32 v173, v169
	s_mov_b64 s[40:41], -1
	v_fma_f32 v67, -v65, v66, 1.0
	v_fmac_f32_e32 v66, v67, v66
	v_div_scale_f32 v67, vcc, 1.0, v64, 1.0
	v_mul_f32_e32 v68, v67, v66
	v_fma_f32 v69, -v65, v68, v67
	v_fmac_f32_e32 v68, v69, v66
	v_fma_f32 v65, -v65, v68, v67
	v_div_fmas_f32 v65, v65, v66, v68
	v_div_fixup_f32 v64, v65, v64, 1.0
	v_pk_mul_f32 v[32:33], v[32:33], v[64:65] op_sel_hi:[1,0]
	v_pk_mul_f32 v[34:35], v[34:35], v[64:65] op_sel_hi:[1,0]
	v_cvt_pk_bf16_f32 v32, v32, v33
	v_cvt_pk_bf16_f32 v33, v34, v35
	v_pk_mul_f32 v[34:35], v[36:37], v[64:65] op_sel_hi:[1,0]
	v_pk_mul_f32 v[36:37], v[38:39], v[64:65] op_sel_hi:[1,0]
	v_lshl_add_u64 v[66:67], s[22:23], 0, v[168:169]
	v_cvt_pk_bf16_f32 v34, v34, v35
	v_cvt_pk_bf16_f32 v35, v36, v37
	v_lshl_add_u64 v[66:67], v[66:67], 0, v[172:173]
	v_permlane32_swap_b32_e32 v32, v34
	v_permlane32_swap_b32_e32 v33, v35
	global_store_dwordx4 v[66:67], v[32:35], off offset:64
	v_pk_mul_f32 v[36:37], v[46:47], v[64:65] op_sel_hi:[1,0]
	v_pk_mul_f32 v[48:49], v[48:49], v[64:65] op_sel_hi:[1,0]
	v_pk_mul_f32 v[32:33], v[40:41], v[64:65] op_sel_hi:[1,0]
	v_pk_mul_f32 v[34:35], v[42:43], v[64:65] op_sel_hi:[1,0]
	v_cvt_pk_bf16_f32 v32, v32, v33
	v_cvt_pk_bf16_f32 v33, v34, v35
	v_pk_mul_f32 v[34:35], v[44:45], v[64:65] op_sel_hi:[1,0]
	v_pk_mul_f32 v[50:51], v[50:51], v[64:65] op_sel_hi:[1,0]
	v_cvt_pk_bf16_f32 v34, v34, v35
	v_cvt_pk_bf16_f32 v35, v36, v37
	v_mov_b32_e32 v36, v179
	s_nop 1
	v_permlane32_swap_b32_e32 v179, v36
	v_add_f32_e32 v36, v179, v36
	v_div_scale_f32 v37, s[4:5], v36, v36, 1.0
	v_rcp_f32_e32 v38, v37
	v_permlane32_swap_b32_e32 v32, v34
	v_permlane32_swap_b32_e32 v33, v35
	global_store_dwordx4 v[66:67], v[32:35], off offset:96
	v_cvt_pk_bf16_f32 v48, v48, v49
	v_cvt_pk_bf16_f32 v49, v50, v51
	v_fma_f32 v32, -v37, v38, 1.0
	v_fmac_f32_e32 v38, v32, v38
	v_div_scale_f32 v32, vcc, 1.0, v36, 1.0
	v_mul_f32_e32 v33, v32, v38
	v_fma_f32 v34, -v37, v33, v32
	v_fmac_f32_e32 v33, v34, v38
	v_fma_f32 v32, -v37, v33, v32
	v_div_fmas_f32 v32, v32, v38, v33
	v_div_fixup_f32 v32, v32, v36, 1.0
	v_pk_mul_f32 v[50:51], v[52:53], v[64:65] op_sel_hi:[1,0]
	v_pk_mul_f32 v[52:53], v[54:55], v[64:65] op_sel_hi:[1,0]
	v_pk_mul_f32 v[0:1], v[0:1], v[32:33] op_sel_hi:[1,0]
	v_pk_mul_f32 v[2:3], v[2:3], v[32:33] op_sel_hi:[1,0]
	v_cvt_pk_bf16_f32 v50, v50, v51
	v_cvt_pk_bf16_f32 v51, v52, v53
	v_pk_mul_f32 v[16:17], v[16:17], v[32:33] op_sel_hi:[1,0]
	v_pk_mul_f32 v[18:19], v[18:19], v[32:33] op_sel_hi:[1,0]
	v_cvt_pk_bf16_f32 v0, v0, v1
	v_cvt_pk_bf16_f32 v1, v2, v3
	v_pk_mul_f32 v[2:3], v[4:5], v[32:33] op_sel_hi:[1,0]
	v_pk_mul_f32 v[4:5], v[6:7], v[32:33] op_sel_hi:[1,0]
	v_permlane32_swap_b32_e32 v48, v50
	v_permlane32_swap_b32_e32 v49, v51
	v_cvt_pk_bf16_f32 v16, v16, v17
	v_cvt_pk_bf16_f32 v17, v18, v19
	v_pk_mul_f32 v[18:19], v[20:21], v[32:33] op_sel_hi:[1,0]
	v_pk_mul_f32 v[20:21], v[22:23], v[32:33] op_sel_hi:[1,0]
	v_cvt_pk_bf16_f32 v2, v2, v3
	v_cvt_pk_bf16_f32 v3, v4, v5
	global_store_dwordx4 v[66:67], v[48:51], off
	v_lshl_add_u64 v[68:69], v[66:67], 0, s[16:17]
	v_cvt_pk_bf16_f32 v18, v18, v19
	v_pk_mul_f32 v[48:49], v[56:57], v[64:65] op_sel_hi:[1,0]
	v_pk_mul_f32 v[50:51], v[58:59], v[64:65] op_sel_hi:[1,0]
	v_cvt_pk_bf16_f32 v19, v20, v21
	v_add_co_u32_e32 v20, vcc, s70, v66
	v_permlane32_swap_b32_e32 v0, v2
	v_permlane32_swap_b32_e32 v1, v3
	v_cvt_pk_bf16_f32 v48, v48, v49
	v_cvt_pk_bf16_f32 v49, v50, v51
	v_pk_mul_f32 v[50:51], v[60:61], v[64:65] op_sel_hi:[1,0]
	v_pk_mul_f32 v[52:53], v[62:63], v[64:65] op_sel_hi:[1,0]
	v_permlane32_swap_b32_e32 v16, v18
	v_permlane32_swap_b32_e32 v17, v19
	v_addc_co_u32_e32 v21, vcc, 0, v67, vcc
	global_store_dwordx4 v[68:69], v[0:3], off offset:64
	v_cvt_pk_bf16_f32 v50, v50, v51
	v_cvt_pk_bf16_f32 v51, v52, v53
	v_pk_mul_f32 v[0:1], v[8:9], v[32:33] op_sel_hi:[1,0]
	global_store_dwordx4 v[20:21], v[16:19], off
	v_cvt_pk_bf16_f32 v64, v0, v1
	v_pk_mul_f32 v[0:1], v[10:11], v[32:33] op_sel_hi:[1,0]
	v_pk_mul_f32 v[16:17], v[24:25], v[32:33] op_sel_hi:[1,0]
	v_pk_mul_f32 v[18:19], v[26:27], v[32:33] op_sel_hi:[1,0]
	v_permlane32_swap_b32_e32 v48, v50
	v_permlane32_swap_b32_e32 v49, v51
	v_cvt_pk_bf16_f32 v16, v16, v17
	v_cvt_pk_bf16_f32 v17, v18, v19
	v_pk_mul_f32 v[18:19], v[28:29], v[32:33] op_sel_hi:[1,0]
	v_pk_mul_f32 v[20:21], v[30:31], v[32:33] op_sel_hi:[1,0]
	v_cvt_pk_bf16_f32 v65, v0, v1
	v_pk_mul_f32 v[0:1], v[12:13], v[32:33] op_sel_hi:[1,0]
	global_store_dwordx4 v[66:67], v[48:51], off offset:32
	v_cvt_pk_bf16_f32 v18, v18, v19
	v_cvt_pk_bf16_f32 v19, v20, v21
	v_cvt_pk_bf16_f32 v66, v0, v1
	v_pk_mul_f32 v[0:1], v[14:15], v[32:33] op_sel_hi:[1,0]
	v_permlane32_swap_b32_e32 v16, v18
	v_permlane32_swap_b32_e32 v17, v19
	v_cvt_pk_bf16_f32 v67, v0, v1
	global_store_dwordx4 v[68:69], v[16:19], off offset:32
	v_permlane32_swap_b32_e32 v64, v66
	v_permlane32_swap_b32_e32 v65, v67
	s_branch .LBB0_456

; __device__ __forceinline__ float bflo(unsigned w) { return __uint_as_float(w << 16); }
; __device__ __forceinline__ float bfhi(unsigned w) { return __uint_as_float(w & 0xffff0000u); }
; __device__ __forceinline__ unsigned pk(float lo, float hi) { f32x2_t v = {lo, hi}; bf16x2_t b = __builtin_convertvector(v, bf16x2_t); return __builtin_bit_cast(unsigned, b); }
;     ...
;         } else {
; #pragma unroll
;             for (int d0 = 0; d0 < 4; ++d0) qf[qb][d0] = __builtin_bit_cast(bf16x8, raw[d0]);
;             float a[8], b[8];
; #pragma unroll
;             for (int j = 0; j < 4; ++j) { a[2 * j] = bflo(raw[ND - 2][j]); a[2 * j + 1] = bfhi(raw[ND - 2][j]); b[2 * j] = bflo(raw[ND - 1][j]); b[2 * j + 1] = bfhi(raw[ND - 1][j]); }
; #pragma unroll
;             for (int j = 0; j < 8; ++j) { __builtin_amdgcn_sched_barrier(0); const float fi = hi ? invf_c(8 + j) : invf_c(j); float c, s; rope_cs(pos, fi, c, s);
;                 const float x1 = a[j], x2 = b[j]; a[j] = x1 * c - x2 * s; b[j] = x2 * c + x1 * s; }
;             u32x4 wa, wb; wa.x = pk(a[0], a[1]); wa.y = pk(a[2], a[3]); wa.z = pk(a[4], a[5]); wa.w = pk(a[6], a[7]); wb.x = pk(b[0], b[1]); wb.y = pk(b[2], b[3]); wb.z = pk(b[4], b[5]); wb.w = pk(b[6], b[7]);
;             qf[qb][ND - 2] = __builtin_bit_cast(bf16x8, wa); qf[qb][ND - 1] = __builtin_bit_cast(bf16x8, wb);
;         }
.LBB0_922:
	s_lshr_b64 s[6:7], s[20:21], 4
	s_lshl_b64 s[8:9], s[6:7], 25
	s_add_u32 s40, s18, s8
	s_addc_u32 s41, s19, s9
	s_add_i32 s9, s59, s50
	s_and_b32 s44, s58, 15
	s_lshr_b32 s8, s9, 4
	s_and_b32 s24, s9, 15
	s_mov_b32 s9, s31
	s_lshl_b32 s30, s44, 13
	s_lshl_b64 s[6:7], s[6:7], 20
	s_lshl_b64 s[10:11], s[8:9], 14
	s_add_u32 s22, s10, s63
	s_addc_u32 s23, s11, s66
	s_mul_i32 s10, s23, 0xc00
	s_mul_hi_u32 s11, s22, 0xc00
	s_add_i32 s11, s11, s10
	s_mul_i32 s10, s22, 0xc00
	s_add_u32 s10, s26, s10
	s_addc_u32 s11, s27, s11
	s_mul_i32 s12, s24, 0xc0
	s_add_u32 s42, s10, s12
	s_addc_u32 s43, s11, 0
	s_lshl_b64 s[12:13], s[8:9], 25
	s_add_u32 s10, s33, s12
	s_addc_u32 s11, s37, s13
	s_lshl_b32 s60, s24, 6
	s_lshl_b32 s35, s24, 7
	s_add_u32 s10, s10, s35
	s_addc_u32 s11, s11, 0
	s_lshl_b64 s[8:9], s[8:9], 20
	s_add_u32 s8, s25, s8
	s_addc_u32 s9, s52, s9
	s_add_u32 s12, s46, s12
	s_addc_u32 s13, s47, s13
	s_lshl_b32 s24, s24, 13
	s_add_u32 s12, s12, s24
	v_mbcnt_lo_u32_b32 v8, -1, 0
	v_mbcnt_hi_u32_b32 v8, -1, v8
	s_addc_u32 s13, s13, 0
	v_and_b32_e32 v237, 63, v8
	v_and_b32_e32 v187, 31, v8
	v_cmp_gt_u32_e32 vcc, 32, v237
	v_mul_u32_u24_e32 v0, 0x600, v187
	v_lshlrev_b32_e32 v96, 1, v0
	v_lshrrev_b32_e32 v2, 1, v8
	v_lshl_add_u64 v[0:1], s[42:43], 0, v[96:97]
	v_and_b32_e32 v96, 16, v2
	v_lshl_add_u64 v[10:11], v[0:1], 0, v[96:97]
	global_load_dwordx4 v[0:3], v[10:11], off offset:128
	global_load_dwordx4 v[4:7], v[10:11], off offset:160
	global_load_dwordx4 v[98:101], v[10:11], off
	global_load_dwordx4 v[102:105], v[10:11], off offset:32
	global_load_dwordx4 v[106:109], v[10:11], off offset:64
	global_load_dwordx4 v[110:113], v[10:11], off offset:96
	v_or_b32_e32 v9, s63, v187
	s_waitcnt vmcnt(5)
	v_and_b32_e32 v18, 0xffff0000, v0
	v_cvt_f32_i32_e32 v9, v9
	s_waitcnt vmcnt(4)
	v_and_b32_e32 v19, 0xffff0000, v4
	v_and_b32_e32 v20, 0xffff0000, v1
	v_and_b32_e32 v21, 0xffff0000, v5
	v_and_b32_e32 v22, 0xffff0000, v2
	v_and_b32_e32 v23, 0xffff0000, v6
	v_and_b32_e32 v24, 0xffff0000, v3
	v_and_b32_e32 v25, 0xffff0000, v7
	v_mov_b32_e32 v10, 0x3c23d70a
	v_cndmask_b32_e64 v27, v10, 1.0, vcc
	v_mul_f32_e32 v10, v27, v9
	v_mul_f32_e32 v11, 0.15915494, v10
	v_rndne_f32_e32 v11, v11
	v_fmac_f32_e32 v10, 0xc0c90fdb, v11
	v_fmac_f32_e32 v10, 0x343bbd2e, v11
	v_mul_f32_e32 v11, 0.15915494, v10
	v_sin_f32_e32 v10, v11
	v_cos_f32_e32 v11, v11
	v_lshlrev_b32_e32 v13, 16, v0
	v_lshlrev_b32_e32 v12, 16, v4
	v_mov_b32_e32 v17, v10
	v_mov_b32_e32 v16, v11
	v_pk_mul_f32 v[14:15], v[10:11], v[12:13]
	v_pk_mul_f32 v[10:11], v[16:17], v[12:13]
	v_mov_b32_e32 v0, 0x3bb8449c
	v_mov_b32_e32 v4, 0x3f0ff59a
	v_cndmask_b32_e32 v29, v0, v4, vcc
	v_mul_f32_e32 v0, v29, v9
	v_mul_f32_e32 v4, 0.15915494, v0
	v_rndne_f32_e32 v4, v4
	v_fmac_f32_e32 v0, 0xc0c90fdb, v4
	v_fmac_f32_e32 v0, 0x343bbd2e, v4
	v_mul_f32_e32 v0, 0.15915494, v0
	v_cos_f32_e32 v4, v0
	v_sin_f32_e32 v0, v0
	v_mov_b32_e32 v12, v15
	v_mov_b32_e32 v16, v11
	v_mul_f32_e32 v13, v4, v18
	v_mul_f32_e32 v15, v0, v19
	v_pk_add_f32 v[12:13], v[12:13], v[14:15] neg_lo:[0,1] neg_hi:[0,1]
	v_mul_f32_e32 v15, v4, v19
	v_mul_f32_e32 v17, v0, v18
	v_mov_b32_e32 v14, v10
	v_pk_add_f32 v[10:11], v[14:15], v[16:17]
	v_mov_b32_e32 v0, 0x3b4f3e37
	v_mov_b32_e32 v4, 0x3ea1e89b
	v_cndmask_b32_e32 v47, v0, v4, vcc
	v_mul_f32_e32 v0, v47, v9
	v_mul_f32_e32 v4, 0.15915494, v0
	v_rndne_f32_e32 v4, v4
	v_fmac_f32_e32 v0, 0xc0c90fdb, v4
	v_fmac_f32_e32 v0, 0x343bbd2e, v4
	v_mul_f32_e32 v0, 0.15915494, v0
	v_sin_f32_e32 v14, v0
	v_cos_f32_e32 v15, v0
	v_lshlrev_b32_e32 v1, 16, v1
	v_lshlrev_b32_e32 v0, 16, v5
	v_mov_b32_e32 v17, v14
	v_mov_b32_e32 v16, v15
	v_pk_mul_f32 v[4:5], v[14:15], v[0:1]
	v_pk_mul_f32 v[0:1], v[16:17], v[0:1]
	v_mov_b32_e32 v14, 0x3ae91528
	v_mov_b32_e32 v15, 0x3e361887
	v_cndmask_b32_e32 v53, v14, v15, vcc
	v_mul_f32_e32 v14, v53, v9
	v_mul_f32_e32 v15, 0.15915494, v14
	v_rndne_f32_e32 v15, v15
	v_fmac_f32_e32 v14, 0xc0c90fdb, v15
	v_fmac_f32_e32 v14, 0x343bbd2e, v15
	v_mul_f32_e32 v14, 0.15915494, v14
	v_cos_f32_e32 v16, v14
	v_sin_f32_e32 v17, v14
	v_mov_b32_e32 v14, v5
	v_mul_f32_e32 v15, v16, v20
	v_mul_f32_e32 v5, v17, v21
	v_pk_add_f32 v[4:5], v[14:15], v[4:5] neg_lo:[0,1] neg_hi:[0,1]
	v_mul_f32_e32 v15, v16, v21
	v_mul_f32_e32 v17, v17, v20
	v_mov_b32_e32 v14, v0
	v_mov_b32_e32 v16, v1
	v_pk_add_f32 v[0:1], v[14:15], v[16:17]
	v_mov_b32_e32 v14, 0x3a83126f
	v_mov_b32_e32 v15, 0x3dcccccd
	v_cndmask_b32_e32 v56, v14, v15, vcc
	v_mul_f32_e32 v14, v56, v9
	v_mul_f32_e32 v15, 0.15915494, v14
	v_rndne_f32_e32 v15, v15
	v_fmac_f32_e32 v14, 0xc0c90fdb, v15
	v_fmac_f32_e32 v14, 0x343bbd2e, v15
	v_mul_f32_e32 v15, 0.15915494, v14
	v_sin_f32_e32 v14, v15
	v_cos_f32_e32 v15, v15
	v_lshlrev_b32_e32 v17, 16, v2
	v_lshlrev_b32_e32 v16, 16, v6
	v_mov_b32_e32 v21, v14
	v_mov_b32_e32 v20, v15
	v_pk_mul_f32 v[18:19], v[14:15], v[16:17]
	v_pk_mul_f32 v[14:15], v[20:21], v[16:17]
	v_mov_b32_e32 v2, 0x3d6655c3
	v_cndmask_b32_e32 v57, v193, v2, vcc
	v_mul_f32_e32 v2, v57, v9
	v_mul_f32_e32 v6, 0.15915494, v2
	v_rndne_f32_e32 v6, v6
	v_fmac_f32_e32 v2, 0xc0c90fdb, v6
	v_fmac_f32_e32 v2, 0x343bbd2e, v6
	v_mul_f32_e32 v2, 0.15915494, v2
	v_cos_f32_e32 v6, v2
	v_sin_f32_e32 v2, v2
	v_mov_b32_e32 v16, v19
	v_mov_b32_e32 v20, v15
	v_mul_f32_e32 v17, v6, v22
	v_mul_f32_e32 v19, v2, v23
	v_pk_add_f32 v[16:17], v[16:17], v[18:19] neg_lo:[0,1] neg_hi:[0,1]
	v_mul_f32_e32 v19, v6, v23
	v_mul_f32_e32 v21, v2, v22
	v_mov_b32_e32 v18, v14
	v_pk_add_f32 v[14:15], v[18:19], v[20:21]
	v_mov_b32_e32 v2, 0x39a5cb5f
	v_mov_b32_e32 v6, 0x3d0186e2
	v_cndmask_b32_e32 v22, v2, v6, vcc
	v_mul_f32_e32 v2, v22, v9
	v_mul_f32_e32 v6, 0.15915494, v2
; __device__ __forceinline__ float bflo(unsigned w) { return __uint_as_float(w << 16); }
; __device__ __forceinline__ float bfhi(unsigned w) { return __uint_as_float(w & 0xffff0000u); }
; __device__ __forceinline__ unsigned pk(float lo, float hi) { f32x2_t v = {lo, hi}; bf16x2_t b = __builtin_convertvector(v, bf16x2_t); return __builtin_bit_cast(unsigned, b); }
; #define BAR_LDS() asm volatile("s_waitcnt lgkmcnt(0)\n\ts_barrier" ::: "memory")
; #define ATT_LOAD(tt) ATT_LOADS(rk, rr, rv, tt)
; #define ATT_STORE(ss) ATT_STORES(rk, rr, rv, ss)
;     ...
;         } else {
; #pragma unroll
;             for (int d0 = 0; d0 < 4; ++d0) qf[qb][d0] = __builtin_bit_cast(bf16x8, raw[d0]);
;             float a[8], b[8];
; #pragma unroll
;             for (int j = 0; j < 4; ++j) { a[2 * j] = bflo(raw[ND - 2][j]); a[2 * j + 1] = bfhi(raw[ND - 2][j]); b[2 * j] = bflo(raw[ND - 1][j]); b[2 * j + 1] = bfhi(raw[ND - 1][j]); }
; #pragma unroll
;             for (int j = 0; j < 8; ++j) { __builtin_amdgcn_sched_barrier(0); const float fi = hi ? invf_c(8 + j) : invf_c(j); float c, s; rope_cs(pos, fi, c, s);
;                 const float x1 = a[j], x2 = b[j]; a[j] = x1 * c - x2 * s; b[j] = x2 * c + x1 * s; }
;             u32x4 wa, wb; wa.x = pk(a[0], a[1]); wa.y = pk(a[2], a[3]); wa.z = pk(a[4], a[5]); wa.w = pk(a[6], a[7]); wb.x = pk(b[0], b[1]); wb.y = pk(b[2], b[3]); wb.z = pk(b[4], b[5]); wb.w = pk(b[6], b[7]);
;             qf[qb][ND - 2] = __builtin_bit_cast(bf16x8, wa); qf[qb][ND - 1] = __builtin_bit_cast(bf16x8, wb);
;         }
; template <int MODE, bool FAST> __device__ __forceinline__ bool attn_unit(LAS unsigned char* lds, const AttU& U, const int wv) {
;     ...
;     const int krow = tid >> 3, kc = tid & 7;
;     const unsigned kgo = (unsigned)(krow * KP + kc * 8) * 2u, krgo = (unsigned)(krow * 32 + kc * 4) * 2u, vgo = (unsigned)tid * 16u;
;     const unsigned kdst = krow * KSTR + kc * 16, krdst = krow * KSTR + 128 + kc * 8, vdst = 64 * KSTR + krow * VSTR + kc * 16;
;     u32x4 rk, rv, rk2, rv2; u32x2 rr = {0u, 0u}, rr2 = {0u, 0u};
;     ...
;     const int NT = U.kt1 - U.kt0;
;     ATT_LOAD(U.kt0); ATT_STORE(0);
;     if (NT > 1) { ATT_LOAD(U.kt0 + 1); ATT_STORE(1); }
;     if (NT > 2) ATT_LOAD(U.kt0 + 2);
;     if constexpr (FAST) { if (NT > 3) ATT_LOADS(rk2, rr2, rv2, U.kt0 + 3); }
;     BAR_LDS();
	v_rndne_f32_e32 v6, v6
	v_fmac_f32_e32 v2, 0xc0c90fdb, v6
	v_fmac_f32_e32 v2, 0x343bbd2e, v6
	v_mul_f32_e32 v2, 0.15915494, v2
	v_sin_f32_e32 v18, v2
	v_cos_f32_e32 v19, v2
	v_lshlrev_b32_e32 v3, 16, v3
	v_lshlrev_b32_e32 v2, 16, v7
	v_mov_b32_e32 v21, v18
	v_mov_b32_e32 v20, v19
	v_pk_mul_f32 v[6:7], v[18:19], v[2:3]
	v_pk_mul_f32 v[2:3], v[20:21], v[2:3]
	v_cndmask_b32_e32 v86, v234, v235, vcc
	v_mul_f32_e32 v9, v86, v9
	v_mul_f32_e32 v18, 0.15915494, v9
	v_rndne_f32_e32 v18, v18
	v_fmac_f32_e32 v9, 0xc0c90fdb, v18
	v_fmac_f32_e32 v9, 0x343bbd2e, v18
	v_mul_f32_e32 v9, 0.15915494, v9
	v_cos_f32_e32 v20, v9
	v_sin_f32_e32 v9, v9
	v_mov_b32_e32 v18, v7
	v_cvt_pk_bf16_f32 v114, v12, v13
	v_mul_f32_e32 v19, v20, v24
	v_mul_f32_e32 v7, v9, v25
	v_pk_add_f32 v[6:7], v[18:19], v[6:7] neg_lo:[0,1] neg_hi:[0,1]
	v_mul_f32_e32 v19, v20, v25
	v_mul_f32_e32 v21, v9, v24
	v_mov_b32_e32 v18, v2
	v_mov_b32_e32 v20, v3
	v_pk_add_f32 v[2:3], v[18:19], v[20:21]
	v_cvt_pk_bf16_f32 v115, v4, v5
	v_cvt_pk_bf16_f32 v116, v16, v17
	v_cvt_pk_bf16_f32 v117, v6, v7
	v_cvt_pk_bf16_f32 v118, v10, v11
	v_cvt_pk_bf16_f32 v119, v0, v1
	v_cvt_pk_bf16_f32 v120, v14, v15
	v_cvt_pk_bf16_f32 v121, v2, v3
	v_or_b32_e32 v9, 32, v237
	v_mul_u32_u24_e32 v0, 0x600, v9
	v_lshlrev_b32_e32 v0, 1, v0
	v_mov_b32_e32 v1, v97
	v_lshl_add_u64 v[0:1], s[42:43], 0, v[0:1]
	v_lshl_add_u64 v[4:5], v[0:1], 0, v[96:97]
	global_load_dwordx4 v[122:125], v[4:5], off
	global_load_dwordx4 v[126:129], v[4:5], off offset:32
	global_load_dwordx4 v[130:133], v[4:5], off offset:64
	global_load_dwordx4 v[134:137], v[4:5], off offset:96
	global_load_dwordx4 v[0:3], v[4:5], off offset:128
	s_nop 0
	global_load_dwordx4 v[4:7], v[4:5], off offset:160
	v_or_b32_e32 v9, s63, v9
	s_nop 0
	v_cvt_f32_i32_e32 v87, v9
	v_add_u32_e32 v9, s36, v8
	v_and_b32_e32 v10, 7, v8
	v_ashrrev_i32_e32 v88, 3, v9
	v_lshlrev_b32_e32 v28, 4, v10
	v_mul_f32_e32 v11, v22, v87
	v_lshl_or_b32 v96, v88, 11, v28
	v_mul_f32_e32 v12, 0.15915494, v11
	v_lshlrev_b32_e32 v89, 3, v10
	v_lshlrev_b32_e32 v66, 6, v88
	v_lshl_add_u64 v[34:35], s[10:11], 0, v[96:97]
	v_rndne_f32_e32 v12, v12
	v_or_b32_e32 v30, v66, v89
	v_mov_b32_e32 v31, v97
	v_add_co_u32_e32 v18, vcc, s39, v34
	v_fmac_f32_e32 v11, 0xc0c90fdb, v12
	v_lshl_add_u64 v[36:37], s[8:9], 0, v[30:31]
	v_addc_co_u32_e32 v19, vcc, 0, v35, vcc
	v_fmac_f32_e32 v11, 0x343bbd2e, v12
	v_lshlrev_b32_e32 v32, 4, v9
	v_mov_b32_e32 v33, v97
	v_add_co_u32_e32 v40, vcc, s92, v36
	v_mul_f32_e32 v46, 0.15915494, v11
	global_load_dwordx4 v[10:13], v96, s[10:11]
	global_load_dwordx4 v[14:17], v32, s[12:13]
	v_lshl_add_u64 v[38:39], s[12:13], 0, v[32:33]
	global_load_dwordx4 v[18:21], v[18:19], off
	v_addc_co_u32_e32 v41, vcc, 0, v37, vcc
	global_load_dwordx2 v[42:43], v30, s[8:9]
	global_load_dwordx2 v[44:45], v[40:41], off offset:-4096
	v_add_co_u32_e32 v22, vcc, s39, v38
	v_mul_f32_e32 v9, v27, v87
	s_nop 0
	v_addc_co_u32_e32 v23, vcc, 0, v39, vcc
	global_load_dwordx4 v[22:25], v[22:23], off
	v_mul_f32_e32 v27, 0.15915494, v9
	v_rndne_f32_e32 v27, v27
	v_fmac_f32_e32 v9, 0xc0c90fdb, v27
	v_fmac_f32_e32 v9, 0x343bbd2e, v27
	v_mul_f32_e32 v9, 0.15915494, v9
	v_cos_f32_e32 v48, v9
	v_sin_f32_e32 v50, v9
	v_mul_f32_e32 v9, v29, v87
	v_mul_f32_e32 v27, 0.15915494, v9
	v_rndne_f32_e32 v27, v27
	v_fmac_f32_e32 v9, 0xc0c90fdb, v27
	v_fmac_f32_e32 v9, 0x343bbd2e, v27
	v_mul_f32_e32 v9, 0.15915494, v9
	v_cos_f32_e32 v49, v9
	v_sin_f32_e32 v51, v9
	v_mul_f32_e32 v9, v47, v87
	v_mul_f32_e32 v27, 0.15915494, v9
	v_rndne_f32_e32 v27, v27
	v_fmac_f32_e32 v9, 0xc0c90fdb, v27
	v_fmac_f32_e32 v9, 0x343bbd2e, v27
	v_mul_f32_e32 v9, 0.15915494, v9
	v_cos_f32_e32 v52, v9
	v_sin_f32_e32 v54, v9
	v_mul_f32_e32 v9, v53, v87
	v_mul_f32_e32 v27, 0.15915494, v9
	v_rndne_f32_e32 v27, v27
	v_fmac_f32_e32 v9, 0xc0c90fdb, v27
	v_fmac_f32_e32 v9, 0x343bbd2e, v27
	v_mul_f32_e32 v9, 0.15915494, v9
	v_cos_f32_e32 v53, v9
	v_sin_f32_e32 v55, v9
	v_mul_f32_e32 v9, v56, v87
	v_mul_f32_e32 v27, 0.15915494, v9
	v_rndne_f32_e32 v27, v27
	v_fmac_f32_e32 v9, 0xc0c90fdb, v27
	v_fmac_f32_e32 v9, 0x343bbd2e, v27
	v_mul_f32_e32 v9, 0.15915494, v9
	v_cos_f32_e32 v56, v9
	v_sin_f32_e32 v58, v9
	v_mul_f32_e32 v9, v57, v87
	v_mul_f32_e32 v27, 0.15915494, v9
	v_rndne_f32_e32 v27, v27
	v_fmac_f32_e32 v9, 0xc0c90fdb, v27
	v_fmac_f32_e32 v9, 0x343bbd2e, v27
	v_mul_lo_u32 v29, v88, s5
	s_mov_b32 s8, 0x60000
	v_mul_f32_e32 v9, 0.15915494, v9
	v_bfe_u32 v27, v8, 5, 1
	v_add_u32_e32 v238, v29, v28
	v_add_co_u32_e32 v8, vcc, s8, v38
	v_cos_f32_e32 v57, v9
	v_sin_f32_e32 v59, v9
	v_addc_co_u32_e32 v9, vcc, 0, v39, vcc
	v_sub_u32_e32 v239, v238, v89
	v_sub_u32_e32 v240, v238, v66
	v_add_u32_e32 v47, 0, v238
	global_load_dwordx4 v[138:141], v[8:9], off
	v_add_u32_e32 v8, 0, v239
	v_add_u32_e32 v9, 0, v240
	global_load_dwordx2 v[188:189], v[40:41], off
	v_lshlrev_b32_e32 v186, 4, v27
	v_mad_u32_u24 v241, v187, s5, v186
	v_add_u32_e32 v242, 0, v241
	s_waitcnt vmcnt(9)
	v_lshlrev_b32_e32 v62, 16, v0
	v_and_b32_e32 v63, 0xffff0000, v0
	s_waitcnt vmcnt(7)
	ds_write_b128 v47, v[10:13]
	v_lshlrev_b32_e32 v60, 16, v4
	v_and_b32_e32 v61, 0xffff0000, v4
	v_pk_mul_f32 v[64:65], v[50:51], v[62:63]
	v_lshlrev_b32_e32 v0, 16, v1
	s_waitcnt vmcnt(4)
	ds_write_b64 v8, v[42:43] offset:128
	ds_write_b128 v9, v[14:17] offset:13312
	ds_write_b128 v47, v[18:21] offset:22528
	s_waitcnt vmcnt(3)
	ds_write_b64 v8, v[44:45] offset:22656
	s_waitcnt vmcnt(2)
	ds_write_b128 v9, v[22:25] offset:35840
	v_add_co_u32_e32 v8, vcc, s4, v34
	v_pk_fma_f32 v[84:85], v[48:49], v[60:61], v[64:65]
	s_nop 0
	v_addc_co_u32_e32 v9, vcc, 0, v35, vcc
	v_add_co_u32_e32 v10, vcc, s4, v38
	v_and_b32_e32 v1, 0xffff0000, v1
	s_nop 0
	v_addc_co_u32_e32 v11, vcc, 0, v39, vcc
	global_load_dwordx4 v[142:145], v[8:9], off
	global_load_dwordx4 v[146:149], v[10:11], off
	v_add_co_u32_e32 v8, vcc, s8, v34
	s_movk_i32 s8, 0x3000
	s_nop 0
	v_addc_co_u32_e32 v9, vcc, 0, v35, vcc
	global_load_dwordx4 v[150:153], v[8:9], off
	v_add_co_u32_e32 v8, vcc, s8, v36
	v_lshlrev_b32_e32 v4, 16, v5
	s_nop 0
	v_addc_co_u32_e32 v9, vcc, 0, v37, vcc
	global_load_dwordx2 v[190:191], v[8:9], off
	s_waitcnt lgkmcnt(0)
	s_barrier
; #define LAS __attribute__((address_space(3)))
; template <int MODE, bool FAST> __device__ __forceinline__ bool attn_unit(LAS unsigned char* lds, const AttU& U, const int wv) {
;     ...
;     const unsigned koff = r32 * KSTR + hi * 16, voff = 64 * KSTR + r32 * VSTR + hi * 16;
;     ...
;     pb[1][0] = (bf16x8){0, 0, 0, 0, 0, 0, 0, 0}; pb[1][1] = pb[1][0];
;     ATT_QK(0, 0, 0);
;     bf16x8 kpre[NPRE > 0 ? NPRE : 1];
; #pragma unroll
;     for (int i_ = 0; i_ < NPRE; ++i_) kpre[i_] = *(LAS const bf16x8*)(lds + koff + i_ * 32);
;     ...
;     if constexpr (FAST) {
;         for (int t2 = U.kt0; t2 < U.kt1; t2 += 2) { ATT_TILE(t2, 4, rk, rr, rv); ATT_TILE(t2 + 1, 4, rk2, rr2, rv2); }
	ds_read_b128 v[80:83], v242
	ds_read_b128 v[174:177], v242 offset:32
	s_waitcnt lgkmcnt(1)
	v_mfma_f32_32x32x16_bf16 v[64:79], v[80:83], v[98:101], 0
	ds_read_b128 v[170:173], v242 offset:64
	v_and_b32_e32 v5, 0xffff0000, v5
	v_mul_f32_e64 v8, v54, v0
	v_mul_f32_e64 v9, v55, v1
	v_lshlrev_b32_e32 v18, 16, v3
	v_pk_fma_f32 v[12:13], v[52:53], v[4:5], v[8:9]
	v_pk_mul_f32 v[4:5], v[54:55], v[4:5]
	v_lshlrev_b32_e32 v8, 16, v2
	s_waitcnt lgkmcnt(1)
	v_mfma_f32_32x32x16_bf16 v[64:79], v[174:177], v[102:105], v[64:79]
	v_and_b32_e32 v9, 0xffff0000, v2
	v_fma_f32 v4, v52, v0, -v4
	v_fma_f32 v5, v53, v1, -v5
	v_lshlrev_b32_e32 v0, 16, v6
	v_and_b32_e32 v1, 0xffff0000, v6
	v_pk_mul_f32 v[10:11], v[58:59], v[8:9]
	v_and_b32_e32 v19, 0xffff0000, v3
	v_pk_fma_f32 v[14:15], v[56:57], v[0:1], v[10:11]
	v_pk_mul_f32 v[0:1], v[58:59], v[0:1]
	v_cos_f32_e32 v26, v46
	v_pk_fma_f32 v[16:17], v[56:57], v[8:9], v[0:1] neg_lo:[0,0,1] neg_hi:[0,0,1]
	ds_read_b128 v[8:11], v242 offset:96
	s_waitcnt lgkmcnt(1)
	v_mfma_f32_32x32x16_bf16 v[64:79], v[170:173], v[106:109], v[64:79]
	v_mul_f32_e32 v0, v86, v87
	v_mul_f32_e32 v1, 0.15915494, v0
	v_rndne_f32_e32 v1, v1
	v_fmac_f32_e32 v0, 0xc0c90fdb, v1
	v_fmac_f32_e32 v0, 0x343bbd2e, v1
	v_mul_f32_e32 v0, 0.15915494, v0
	v_sin_f32_e32 v47, v0
	v_cos_f32_e32 v27, v0
	ds_read_b128 v[0:3], v242 offset:128
	s_waitcnt lgkmcnt(1)
	v_mfma_f32_32x32x16_bf16 v[64:79], v[8:11], v[110:113], v[64:79]
	v_sin_f32_e32 v46, v46
	v_lshlrev_b32_e32 v6, 16, v7
	v_and_b32_e32 v7, 0xffff0000, v7
	v_cvt_pk_bf16_f32 v155, v4, v5
	v_pk_mul_f32 v[8:9], v[46:47], v[18:19]
	v_pk_mul_f32 v[50:51], v[50:51], v[60:61]
	v_pk_fma_f32 v[8:9], v[26:27], v[6:7], v[8:9]
	v_pk_mul_f32 v[6:7], v[46:47], v[6:7]
	v_pk_fma_f32 v[48:49], v[48:49], v[62:63], v[50:51] neg_lo:[0,0,1] neg_hi:[0,0,1]
	v_pk_fma_f32 v[10:11], v[26:27], v[18:19], v[6:7] neg_lo:[0,0,1] neg_hi:[0,0,1]
	ds_read_b128 v[4:7], v242 offset:160
	s_waitcnt lgkmcnt(1)
	v_mfma_f32_32x32x16_bf16 v[64:79], v[0:3], v[114:117], v[64:79]
	v_lshlrev_b32_e32 v0, 6, v187
	s_add_u32 s6, s56, s6
	v_cvt_pk_bf16_f32 v154, v48, v49
	v_sub_u32_e32 v243, v241, v0
	s_addc_u32 s7, s57, s7
	v_mov_b32_e32 v48, 0
	v_cvt_pk_bf16_f32 v156, v16, v17
	s_waitcnt lgkmcnt(0)
	v_mfma_f32_32x32x16_bf16 v[64:79], v[4:7], v[118:121], v[64:79]
	v_cvt_pk_bf16_f32 v157, v10, v11
	v_cvt_pk_bf16_f32 v158, v84, v85
	v_cvt_pk_bf16_f32 v159, v12, v13
	v_cvt_pk_bf16_f32 v160, v14, v15
	v_cvt_pk_bf16_f32 v161, v8, v9
	v_add_u32_e32 v244, 0, v243
	v_add_u32_e32 v245, v89, v29
	v_mad_u64_u32 v[198:199], s[8:9], v88, s69, v[28:29]
	v_lshl_or_b32 v96, s44, 7, v96
	v_mov_b32_e32 v200, v32
	s_add_u32 s98, s40, 0x12380000
	s_addc_u32 s99, s41, 0
	s_add_u32 s100, s40, s30
	s_addc_u32 s101, s41, s31
	s_add_u32 s100, s100, 0x18380000
	s_addc_u32 s101, s101, 0
	v_lshl_add_u64 v[202:203], s[6:7], 0, v[30:31]
	s_mov_b64 s[42:43], 0
	v_mov_b32_e32 v162, 0
	v_mov_b32_e32 v163, 0
	v_mov_b32_e32 v164, 0
	v_mov_b32_e32 v165, 0
	v_mov_b32_e32 v166, 0
	v_mov_b32_e32 v167, 0
	v_mov_b32_e32 v168, 0
	v_mov_b32_e32 v169, 0
	s_mov_b32 s61, 0
	v_mov_b32_e32 v49, v48
	v_mov_b32_e32 v50, v48
	v_mov_b32_e32 v51, v48
	v_mov_b32_e32 v52, v48
	v_mov_b32_e32 v53, v48
	v_mov_b32_e32 v54, v48
	v_mov_b32_e32 v55, v48
	v_mov_b32_e32 v56, v48
	v_mov_b32_e32 v57, v48
	v_mov_b32_e32 v58, v48
	v_mov_b32_e32 v59, v48
	v_mov_b32_e32 v60, v48
	v_mov_b32_e32 v61, v48
	v_mov_b32_e32 v62, v48
	v_mov_b32_e32 v63, v48
	v_mov_b32_e32 v32, v48
	v_mov_b32_e32 v33, v48
	v_mov_b32_e32 v34, v48
	v_mov_b32_e32 v35, v48
	v_mov_b32_e32 v36, v48
	v_mov_b32_e32 v37, v48
	v_mov_b32_e32 v38, v48
	v_mov_b32_e32 v39, v48
	v_mov_b32_e32 v40, v48
	v_mov_b32_e32 v41, v48
	v_mov_b32_e32 v42, v48
	v_mov_b32_e32 v43, v48
	v_mov_b32_e32 v44, v48
	v_mov_b32_e32 v45, v48
	v_mov_b32_e32 v46, v48
	v_mov_b32_e32 v47, v48
	v_mov_b32_e32 v16, v48
	v_mov_b32_e32 v17, v48
	v_mov_b32_e32 v18, v48
	v_mov_b32_e32 v19, v48
	v_mov_b32_e32 v20, v48
	v_mov_b32_e32 v21, v48
	v_mov_b32_e32 v22, v48
	v_mov_b32_e32 v23, v48
	v_mov_b32_e32 v24, v48
	v_mov_b32_e32 v25, v48
	v_mov_b32_e32 v26, v48
	v_mov_b32_e32 v27, v48
	v_mov_b32_e32 v28, v48
	v_mov_b32_e32 v29, v48
	v_mov_b32_e32 v30, v48
	v_mov_b32_e32 v31, v48
	v_mov_b32_e32 v0, v48
	v_mov_b32_e32 v1, v48
	v_mov_b32_e32 v2, v48
	v_mov_b32_e32 v3, v48
	v_mov_b32_e32 v4, v48
	v_mov_b32_e32 v5, v48
	v_mov_b32_e32 v6, v48
	v_mov_b32_e32 v7, v48
	v_mov_b32_e32 v8, v48
	v_mov_b32_e32 v9, v48
	v_mov_b32_e32 v10, v48
	v_mov_b32_e32 v11, v48
	v_mov_b32_e32 v12, v48
	v_mov_b32_e32 v13, v48
	v_mov_b32_e32 v14, v48
	v_mov_b32_e32 v15, v48
	v_mov_b32_e32 v204, v48
	v_mov_b32_e32 v205, v48
	s_bitcmp1_b32 s36, 8
	s_cbranch_scc0 .Lprio_mla
	s_setprio 1
.Lprio_mla:
.LBB0_923:
	s_add_i32 s30, s61, 2
	s_cmpk_gt_u32 s61, 0xfd
	s_cselect_b64 s[44:45], -1, 0
	s_and_b64 vcc, exec, s[44:45]
	s_cbranch_vccnz .LBB0_925
	s_and_b32 s6, s30, 2
	s_mulk_i32 s6, 0x5800
	s_add_i32 s6, s6, 0
	v_add_u32_e32 v84, s6, v238
	v_add_u32_e32 v85, s6, v239
	v_add_u32_e32 v86, s6, v240
	s_waitcnt vmcnt(1)
	ds_write_b128 v84, v[142:145]
	ds_write_b64 v85, v[188:189] offset:128
	s_waitcnt vmcnt(0)
	ds_write_b128 v86, v[146:149] offset:13312

; #define LAS __attribute__((address_space(3)))
; #define BAR_LDS() asm volatile("s_waitcnt lgkmcnt(0)\n\ts_barrier" ::: "memory")
; #define ATT_PV(Y, sp, kh) do { LAS const unsigned char* vp_ = lds + (sp) * STG + voff + (kh) * 64; \
;         _Pragma("unroll") for (int db = 0; db < 2; ++db) _Pragma("unroll") for (int ks = 0; ks < 2; ++ks) \
;             o[Y][db] = MFMA32(*(LAS const bf16x8*)(vp_ + db * 32 * VSTR + ks * 32), pb[Y][ks], o[Y][db]); } while (0)
; template <int MODE, bool FAST> __device__ __forceinline__ bool attn_unit(LAS unsigned char* lds, const AttU& U, const int wv) {
;     ...
;     ATT_PV(1, (NT - 1) & 3, 1);
;     BAR_LDS();
;     ...
;     if constexpr (FAST) {
;         volatile LAS unsigned* vote = (volatile LAS unsigned*)(lds + 131072 + 64);
;         if (lane == 0) vote[wv] = bad_ ? 1u : 0u;
.LBB0_937:
	s_setprio 0
	v_mul_u32_u24_e32 v64, 0x90, v187
	v_add3_u32 v68, v64, v186, s68
	ds_read_b128 v[64:67], v68 offset:13376
	v_cmp_eq_u32_e32 vcc, 0, v237
	s_waitcnt lgkmcnt(0)
	v_mfma_f32_32x32x16_bf16 v[16:31], v[64:67], v[162:165], v[16:31]
	ds_read_b128 v[64:67], v68 offset:13408
	s_waitcnt lgkmcnt(0)
	v_mfma_f32_32x32x16_bf16 v[16:31], v[64:67], v[166:169], v[16:31]
	ds_read_b128 v[64:67], v68 offset:17984
	s_waitcnt lgkmcnt(0)
	v_mfma_f32_32x32x16_bf16 v[0:15], v[64:67], v[162:165], v[0:15]
	ds_read_b128 v[64:67], v68 offset:18016
	s_waitcnt lgkmcnt(0)
	s_barrier
	s_waitcnt lgkmcnt(0)
	v_mfma_f32_32x32x16_bf16 v[0:15], v[64:67], v[166:169], v[0:15]
	s_and_saveexec_b64 s[6:7], vcc
	s_cbranch_execz .LBB0_920
	v_cndmask_b32_e64 v64, 0, 1, s[42:43]
	v_mov_b32_e32 v65, s96
	ds_write_b32 v65, v64
	s_branch .LBB0_920
